# plus: W_in epilogue: rope and LN parameter loads hoisted and pipelined (gains loaded once per tile, rope rows one group ahead)
# speedup vs baseline: 1.0122x; 1.0004x over previous
.LBB0_137:
	s_lshl_b32 s47, s60, 8
	s_add_i32 s47, s47, s48
	v_add_u32_e32 v158, s47, v128
	v_ashrrev_i32_e32 v159, 31, v158
	s_lshl_b32 s84, s24, 8
	v_lshlrev_b64 v[128:129], 12, v[158:159]
	s_ashr_i32 s85, s84, 31
	v_lshl_add_u64 v[128:129], s[50:51], 0, v[128:129]
	v_lshl_add_u64 v[128:129], s[84:85], 1, v[128:129]
	v_lshlrev_b32_e32 v160, 3, v187
	v_lshl_add_u64 v[128:129], v[128:129], 0, s[74:75]
	v_ashrrev_i32_e32 v161, 31, v160
	s_mov_b64 s[54:55], -1
	s_andn2_b64 vcc, exec, s[80:81]
	v_lshl_add_u64 v[156:157], v[160:161], 1, v[128:129]
	s_movk_i32 s85, 0x3dff
	s_cbranch_vccz .LBB0_150
	s_and_b64 vcc, exec, s[16:17]
	s_cbranch_vccz .LBB0_155
	s_xor_b64 s[54:55], s[78:79], -1
	s_mov_b64 s[16:17], -1
	s_and_b64 vcc, exec, s[54:55]
	s_cbranch_vccz .LBB0_145
	v_mul_f32_e32 v128, v124, v124
	v_fmamk_f32 v128, v128, 0xbdd2d3e7, v252
	v_mul_f32_e32 v128, v124, v128
	v_exp_f32_e32 v128, v128
	s_xor_b64 s[54:55], s[76:77], -1
	v_mul_f32_e32 v129, v126, v126
	v_mul_f32_e32 v130, v120, v120
	v_add_f32_e32 v128, 1.0, v128
	v_rcp_f32_e32 v128, v128
	v_mul_f32_e32 v131, v122, v122
	v_mul_f32_e32 v132, v114, v114
	v_mul_f32_e32 v133, v104, v104
	v_mul_f32_e32 v199, v124, v128
	v_mul_f32_e32 v128, v112, v112
	v_mul_f32_e32 v134, v106, v106
	v_mul_f32_e32 v135, v116, v116
	v_mul_f32_e32 v136, v118, v118
	v_mul_f32_e32 v137, v108, v108
	v_mul_f32_e32 v138, v110, v110
	v_mul_f32_e32 v139, v96, v96
	v_mul_f32_e32 v140, v98, v98
	v_mul_f32_e32 v141, v88, v88
	v_mul_f32_e32 v142, v90, v90
	v_mov_b32_e32 v210, 0x7fc00000
	v_mov_b32_e32 v215, 0xbab64f3b
	v_mov_b32_e32 v214, 0x3c0881c4
	s_and_b64 vcc, exec, s[54:55]
	v_fmamk_f32 v220, v129, 0xbdd2d3e7, v252
	v_fmamk_f32 v219, v130, 0xbdd2d3e7, v252
	v_fmamk_f32 v205, v131, 0xbdd2d3e7, v252
	v_fmamk_f32 v204, v128, 0xbdd2d3e7, v252
	v_fmamk_f32 v203, v132, 0xbdd2d3e7, v252
	v_fmamk_f32 v202, v133, 0xbdd2d3e7, v252
	v_fmamk_f32 v201, v134, 0xbdd2d3e7, v252
	v_fmamk_f32 v200, v135, 0xbdd2d3e7, v252
	v_fmamk_f32 v198, v136, 0xbdd2d3e7, v252
	v_fmamk_f32 v197, v137, 0xbdd2d3e7, v252
	v_fmamk_f32 v196, v138, 0xbdd2d3e7, v252
	v_fmamk_f32 v195, v139, 0xbdd2d3e7, v252
	v_fmamk_f32 v194, v140, 0xbdd2d3e7, v252
	v_fmamk_f32 v192, v141, 0xbdd2d3e7, v252
	v_fmamk_f32 v188, v142, 0xbdd2d3e7, v252
	v_mul_f32_e32 v159, v100, v100
	s_cbranch_vccz .LBB0_142
	v_mul_f32_e32 v135, v113, v113
	v_fmamk_f32 v135, v135, 0xbdd2d3e7, v252
	v_mul_f32_e32 v134, v112, v204
	v_mul_f32_e32 v135, v113, v135
	v_exp_f32_e32 v134, v134
	v_exp_f32_e32 v135, v135
	v_mul_f32_e32 v128, v125, v125
	v_fmamk_f32 v128, v128, 0xbdd2d3e7, v252
	v_add_f32_e32 v134, 1.0, v134
	v_add_f32_e32 v135, 1.0, v135
	v_rcp_f32_e32 v134, v134
	v_rcp_f32_e32 v135, v135
	v_mul_f32_e32 v128, v125, v128
	v_mul_f32_e32 v129, v126, v220
	v_exp_f32_e32 v128, v128
	v_pk_mul_f32 v[166:167], v[112:113], v[134:135]
	v_mul_f32_e32 v135, v115, v115
	v_fmamk_f32 v135, v135, 0xbdd2d3e7, v252
	v_mul_f32_e32 v134, v114, v203
	v_mul_f32_e32 v135, v115, v135
	v_exp_f32_e32 v134, v134
	v_exp_f32_e32 v135, v135
	v_exp_f32_e32 v129, v129
	v_add_f32_e32 v128, 1.0, v128
	v_add_f32_e32 v134, 1.0, v134
	v_add_f32_e32 v135, 1.0, v135
	v_rcp_f32_e32 v134, v134
	v_rcp_f32_e32 v135, v135
	v_add_f32_e32 v129, 1.0, v129
	v_rcp_f32_e32 v128, v128
	v_rcp_f32_e32 v129, v129
	v_pk_mul_f32 v[168:169], v[114:115], v[134:135]
	v_mul_f32_e32 v135, v105, v105
	v_fmamk_f32 v135, v135, 0xbdd2d3e7, v252
	v_mul_f32_e32 v134, v104, v202
	v_mul_f32_e32 v135, v105, v135
	v_exp_f32_e32 v134, v134
	v_exp_f32_e32 v135, v135
	v_mov_b32_e32 v130, v125
	v_mov_b32_e32 v131, v126
	v_pk_mul_f32 v[128:129], v[130:131], v[128:129]
	v_mul_f32_e32 v130, v127, v127
	v_fmamk_f32 v130, v130, 0xbdd2d3e7, v252
	v_add_f32_e32 v134, 1.0, v134
	v_add_f32_e32 v135, 1.0, v135
	v_mul_f32_e32 v130, v127, v130
	v_rcp_f32_e32 v134, v134
	v_rcp_f32_e32 v135, v135
	v_exp_f32_e32 v130, v130
	v_mul_f32_e32 v131, v121, v121
	v_mul_f32_e32 v133, v123, v123
	v_pk_mul_f32 v[170:171], v[104:105], v[134:135]
	v_mul_f32_e32 v135, v107, v107
	v_add_f32_e32 v130, 1.0, v130
	v_fmamk_f32 v131, v131, 0xbdd2d3e7, v252
	v_fmamk_f32 v133, v133, 0xbdd2d3e7, v252
	v_fmamk_f32 v135, v135, 0xbdd2d3e7, v252
	v_rcp_f32_e32 v136, v130
	v_mul_f32_e32 v130, v120, v219
	v_mul_f32_e32 v131, v121, v131
	v_mul_f32_e32 v132, v122, v205
	v_mul_f32_e32 v133, v123, v133
	v_mul_f32_e32 v134, v106, v201
	v_mul_f32_e32 v135, v107, v135
	v_exp_f32_e32 v130, v130
	v_exp_f32_e32 v131, v131
	v_exp_f32_e32 v132, v132
	v_exp_f32_e32 v133, v133
	v_exp_f32_e32 v134, v134
	v_exp_f32_e32 v135, v135
	v_add_f32_e32 v130, 1.0, v130
	v_add_f32_e32 v131, 1.0, v131
	v_add_f32_e32 v132, 1.0, v132
	v_add_f32_e32 v133, 1.0, v133
	v_add_f32_e32 v134, 1.0, v134
	v_add_f32_e32 v135, 1.0, v135
	v_rcp_f32_e32 v130, v130
	v_rcp_f32_e32 v131, v131
	v_rcp_f32_e32 v132, v132
	v_rcp_f32_e32 v133, v133
	v_rcp_f32_e32 v134, v134
	v_rcp_f32_e32 v135, v135
	v_pk_mul_f32 v[130:131], v[120:121], v[130:131]
	v_pk_mul_f32 v[132:133], v[122:123], v[132:133]
	v_add_f32_e32 v137, v130, v131
	v_pk_mul_f32 v[172:173], v[106:107], v[134:135]
	v_add_f32_e32 v134, v199, v128
	v_fma_f32 v135, v127, v136, v129
	v_add_f32_e32 v134, v134, v135
	v_add_f32_e32 v135, v132, v133
	v_add_f32_e32 v134, 0, v134
	v_add_f32_e32 v135, v137, v135
	v_add_f32_e32 v134, v134, v135
	v_add_f32_e32 v135, v168, v169
	v_add_f32_e32 v137, v166, v167
	v_add_f32_e32 v135, v137, v135
	v_add_f32_e32 v134, v134, v135
	v_add_f32_e32 v135, v172, v173
	v_add_f32_e32 v137, v170, v171
	v_add_f32_e32 v135, v137, v135
	v_add_f32_e32 v134, v134, v135
	v_mov_b32_e32 v135, v134
	s_nop 1
	v_permlane16_swap_b32_e32 v134, v135
	v_add_f32_e32 v134, v134, v135
	v_mov_b32_e32 v135, v134
	s_nop 1
	v_permlane32_swap_b32_e32 v134, v135
	v_add_f32_e32 v137, v134, v135
	v_mul_f32_e32 v135, 0xbc800000, v137
	v_fmac_f32_e32 v135, v127, v136
	v_fmac_f32_e32 v128, 0xbc800000, v137
	v_fmamk_f32 v134, v137, 0xbc800000, v129
	v_fmamk_f32 v136, v137, 0xbc800000, v199
	v_mul_f32_e32 v129, v128, v128
	v_mul_f32_e32 v138, v135, v135
	v_fmac_f32_e32 v129, v136, v136
	v_fmac_f32_e32 v138, v134, v134
	v_fmac_f32_e32 v133, 0xbc800000, v137
	v_fmac_f32_e32 v131, 0xbc800000, v137
	v_add_f32_e32 v129, v129, v138
	v_fmamk_f32 v132, v137, 0xbc800000, v132
	v_fmamk_f32 v130, v137, 0xbc800000, v130
	v_mul_f32_e32 v138, v131, v131
	v_mul_f32_e32 v139, v133, v133
	v_fmac_f32_e32 v138, v130, v130
	v_fmac_f32_e32 v139, v132, v132
	v_add_f32_e32 v138, v138, v139
	v_fmac_f32_e32 v169, 0xbc800000, v137
	v_fmac_f32_e32 v167, 0xbc800000, v137
	v_add_f32_e32 v129, v129, v138
	v_fmamk_f32 v168, v137, 0xbc800000, v168
	v_fmamk_f32 v166, v137, 0xbc800000, v166
	v_mul_f32_e32 v138, v167, v167
	v_mul_f32_e32 v139, v169, v169
	v_fmac_f32_e32 v138, v166, v166
	v_fmac_f32_e32 v139, v168, v168
	v_add_f32_e32 v138, v138, v139
	v_fmac_f32_e32 v173, 0xbc800000, v137
	v_fmac_f32_e32 v171, 0xbc800000, v137
	v_add_f32_e32 v129, v138, v129
	v_fmamk_f32 v172, v137, 0xbc800000, v172
	v_fmamk_f32 v170, v137, 0xbc800000, v170
	v_mul_f32_e32 v137, v171, v171
	v_mul_f32_e32 v138, v173, v173
	v_fmac_f32_e32 v137, v170, v170
	v_fmac_f32_e32 v138, v172, v172
	v_readlane_b32 s16, v255, 28
	v_add_f32_e32 v137, v137, v138
	v_lshlrev_b64 v[138:139], 2, v[160:161]
	v_readlane_b32 s17, v255, 29
	v_add_f32_e32 v129, v137, v129
	v_mov_b32_e32 v137, v129
	v_lshl_add_u64 v[162:163], s[16:17], 0, v[138:139]
	v_readlane_b32 s16, v255, 30
	v_readlane_b32 s17, v255, 31
	v_permlane16_swap_b32_e32 v129, v137
	s_nop 0
	v_lshl_add_u64 v[164:165], s[16:17], 0, v[138:139]
	global_load_dwordx4 v[228:231], v[162:163], off offset:16
	global_load_dwordx4 v[232:235], v[162:163], off
	global_load_dwordx4 v[206:209], v[164:165], off offset:16
	global_load_dwordx4 v[236:239], v[164:165], off
	global_load_dwordx4 v[240:243], v[162:163], off offset:144
	global_load_dwordx4 v[244:247], v[162:163], off offset:128
	global_load_dwordx4 v[248:251], v[164:165], off offset:144
	global_load_dwordx4 v[222:225], v[164:165], off offset:128
	s_nop 0
	v_add_f32_e32 v129, v129, v137
	v_mov_b32_e32 v137, v129
	s_nop 1
	v_permlane32_swap_b32_e32 v129, v137
	v_add_f32_e32 v129, v129, v137
	v_fmamk_f32 v129, v129, 0x3c800000, v191
	v_rsq_f32_e32 v174, v129
	v_mov_b32_e32 v137, v128
	s_mov_b32 s16, 0x10000
	v_pk_mul_f32 v[128:129], v[136:137], v[174:175] op_sel_hi:[1,0]
	v_pk_mul_f32 v[134:135], v[134:135], v[174:175] op_sel_hi:[1,0]
	v_pk_mul_f32 v[166:167], v[166:167], v[174:175] op_sel_hi:[1,0]
	v_pk_mul_f32 v[168:169], v[168:169], v[174:175] op_sel_hi:[1,0]
	s_waitcnt vmcnt(0)
	v_pk_fma_f32 v[178:179], v[234:235], v[134:135], v[238:239]
	v_pk_fma_f32 v[182:183], v[232:233], v[128:129], v[236:237]
	v_pk_mul_f32 v[128:129], v[130:131], v[174:175] op_sel_hi:[1,0]
	v_pk_mul_f32 v[130:131], v[132:133], v[174:175] op_sel_hi:[1,0]
	v_pk_fma_f32 v[180:181], v[228:229], v[128:129], v[206:207]
	v_pk_fma_f32 v[176:177], v[230:231], v[130:131], v[208:209]
	s_nop 0
	v_pk_fma_f32 v[136:137], v[244:245], v[166:167], v[222:223]
	v_pk_mul_f32 v[140:141], v[170:171], v[174:175] op_sel_hi:[1,0]
	v_pk_fma_f32 v[138:139], v[246:247], v[168:169], v[224:225]
	v_pk_mul_f32 v[142:143], v[172:173], v[174:175] op_sel_hi:[1,0]
	v_pk_fma_f32 v[132:133], v[240:241], v[140:141], v[248:249]
	v_cvt_pk_bf16_f32 v128, v182, v183
	v_pk_fma_f32 v[134:135], v[242:243], v[142:143], v[250:251]
	v_cvt_pk_bf16_f32 v129, v178, v179
	v_cvt_pk_bf16_f32 v130, v180, v181
	v_cvt_pk_bf16_f32 v131, v176, v177
	global_store_dwordx4 v[156:157], v[128:131], off
	s_nop 1
	v_cvt_pk_bf16_f32 v128, v136, v137
	v_mul_f32_e32 v137, v97, v97
	v_fmamk_f32 v137, v137, 0xbdd2d3e7, v252
	v_mul_f32_e32 v136, v96, v195
	v_mul_f32_e32 v137, v97, v137
	v_exp_f32_e32 v136, v136
	v_exp_f32_e32 v137, v137
	v_cvt_pk_bf16_f32 v129, v138, v139
	v_cvt_pk_bf16_f32 v130, v132, v133
	v_add_f32_e32 v136, 1.0, v136
	v_add_f32_e32 v137, 1.0, v137
	v_rcp_f32_e32 v136, v136
	v_rcp_f32_e32 v137, v137
	v_cvt_pk_bf16_f32 v131, v134, v135
	global_store_dwordx4 v[156:157], v[128:131], off offset:64
	v_mul_f32_e32 v133, v109, v109
	v_pk_mul_f32 v[166:167], v[96:97], v[136:137]
	v_mul_f32_e32 v137, v99, v99
	v_fmamk_f32 v137, v137, 0xbdd2d3e7, v252
	v_mul_f32_e32 v136, v98, v194
	v_mul_f32_e32 v137, v99, v137
	v_exp_f32_e32 v136, v136
	v_exp_f32_e32 v137, v137
	v_mul_f32_e32 v129, v117, v117
	v_mul_f32_e32 v131, v119, v119
	v_add_f32_e32 v136, 1.0, v136
	v_add_f32_e32 v137, 1.0, v137
	v_rcp_f32_e32 v136, v136
	v_rcp_f32_e32 v137, v137
	v_fmamk_f32 v129, v129, 0xbdd2d3e7, v252
	v_fmamk_f32 v131, v131, 0xbdd2d3e7, v252
	v_mul_f32_e32 v135, v111, v111
	v_pk_mul_f32 v[168:169], v[98:99], v[136:137]
	v_mul_f32_e32 v137, v89, v89
	v_fmamk_f32 v137, v137, 0xbdd2d3e7, v252
	v_mul_f32_e32 v136, v88, v192
	v_mul_f32_e32 v137, v89, v137
	v_exp_f32_e32 v136, v136
	v_exp_f32_e32 v137, v137
	v_mul_f32_e32 v128, v116, v200
	v_mul_f32_e32 v129, v117, v129
	v_add_f32_e32 v136, 1.0, v136
	v_add_f32_e32 v137, 1.0, v137
	v_rcp_f32_e32 v136, v136
	v_rcp_f32_e32 v137, v137
	v_mul_f32_e32 v130, v118, v198
	v_mul_f32_e32 v131, v119, v131
	v_fmamk_f32 v133, v133, 0xbdd2d3e7, v252
	v_pk_mul_f32 v[170:171], v[88:89], v[136:137]
	v_mul_f32_e32 v137, v91, v91
	v_fmamk_f32 v135, v135, 0xbdd2d3e7, v252
	v_fmamk_f32 v137, v137, 0xbdd2d3e7, v252
	v_exp_f32_e32 v128, v128
	v_exp_f32_e32 v129, v129
	v_exp_f32_e32 v130, v130
	v_exp_f32_e32 v131, v131
	v_mul_f32_e32 v132, v108, v197
	v_mul_f32_e32 v133, v109, v133
	v_mul_f32_e32 v134, v110, v196
	v_mul_f32_e32 v135, v111, v135
	v_mul_f32_e32 v136, v90, v188
	v_mul_f32_e32 v137, v91, v137
	v_exp_f32_e32 v132, v132
	v_exp_f32_e32 v133, v133
	v_exp_f32_e32 v134, v134
	v_exp_f32_e32 v135, v135
	v_exp_f32_e32 v136, v136
	v_exp_f32_e32 v137, v137
	v_add_f32_e32 v128, 1.0, v128
	v_add_f32_e32 v129, 1.0, v129
	v_add_f32_e32 v130, 1.0, v130
	v_add_f32_e32 v131, 1.0, v131
	v_rcp_f32_e32 v128, v128
	v_rcp_f32_e32 v129, v129
	v_rcp_f32_e32 v130, v130
	v_rcp_f32_e32 v131, v131
	v_add_f32_e32 v132, 1.0, v132
	v_add_f32_e32 v133, 1.0, v133
	v_add_f32_e32 v134, 1.0, v134
	v_add_f32_e32 v135, 1.0, v135
	v_add_f32_e32 v136, 1.0, v136
	v_add_f32_e32 v137, 1.0, v137
	v_rcp_f32_e32 v132, v132
	v_rcp_f32_e32 v133, v133
	v_rcp_f32_e32 v134, v134
	v_rcp_f32_e32 v135, v135
	v_rcp_f32_e32 v136, v136
	v_rcp_f32_e32 v137, v137
	v_pk_mul_f32 v[128:129], v[116:117], v[128:129]
	v_pk_mul_f32 v[130:131], v[118:119], v[130:131]
	v_pk_mul_f32 v[132:133], v[108:109], v[132:133]
	v_pk_mul_f32 v[134:135], v[110:111], v[134:135]
	v_pk_mul_f32 v[172:173], v[90:91], v[136:137]
	v_add_f32_e32 v136, v130, v131
	v_add_f32_e32 v137, v128, v129
	v_add_f32_e32 v136, v137, v136
	v_add_f32_e32 v137, v134, v135
	v_add_f32_e32 v138, v132, v133
	v_add_f32_e32 v136, 0, v136
	v_add_f32_e32 v137, v138, v137
	v_add_f32_e32 v136, v136, v137
	v_add_f32_e32 v137, v168, v169
	v_add_f32_e32 v138, v166, v167
	v_add_f32_e32 v137, v138, v137
	v_add_f32_e32 v136, v136, v137
	v_add_f32_e32 v137, v172, v173
	v_add_f32_e32 v138, v170, v171
	v_add_f32_e32 v137, v138, v137
	v_add_f32_e32 v136, v136, v137
	v_mov_b32_e32 v137, v136
	s_nop 1
	v_permlane16_swap_b32_e32 v136, v137
	v_add_f32_e32 v136, v136, v137
	v_mov_b32_e32 v137, v136
	s_nop 1
	v_permlane32_swap_b32_e32 v136, v137
	v_add_f32_e32 v136, v136, v137
	v_fmac_f32_e32 v131, 0xbc800000, v136
	v_fmac_f32_e32 v129, 0xbc800000, v136
	v_fmamk_f32 v130, v136, 0xbc800000, v130
	v_fmamk_f32 v128, v136, 0xbc800000, v128
	v_mul_f32_e32 v137, v129, v129
	v_mul_f32_e32 v138, v131, v131
	v_fmac_f32_e32 v137, v128, v128
	v_fmac_f32_e32 v138, v130, v130
	v_fmac_f32_e32 v135, 0xbc800000, v136
	v_fmac_f32_e32 v133, 0xbc800000, v136
	v_add_f32_e32 v137, v137, v138
	v_fmamk_f32 v134, v136, 0xbc800000, v134
	v_fmamk_f32 v132, v136, 0xbc800000, v132
	v_mul_f32_e32 v138, v133, v133
	v_mul_f32_e32 v139, v135, v135
	v_fmac_f32_e32 v138, v132, v132
	v_fmac_f32_e32 v139, v134, v134
	v_add_f32_e32 v138, v138, v139
	v_fmac_f32_e32 v169, 0xbc800000, v136
	v_fmac_f32_e32 v167, 0xbc800000, v136
	v_add_f32_e32 v137, v137, v138
	v_fmamk_f32 v168, v136, 0xbc800000, v168
	v_fmamk_f32 v166, v136, 0xbc800000, v166
	v_mul_f32_e32 v138, v167, v167
	v_mul_f32_e32 v139, v169, v169
	v_fmac_f32_e32 v138, v166, v166
	v_fmac_f32_e32 v139, v168, v168
	v_add_f32_e32 v138, v138, v139
	v_fmac_f32_e32 v173, 0xbc800000, v136
	v_fmac_f32_e32 v171, 0xbc800000, v136
	v_add_f32_e32 v137, v138, v137
	v_fmamk_f32 v172, v136, 0xbc800000, v172
	v_fmamk_f32 v170, v136, 0xbc800000, v170
	v_mul_f32_e32 v136, v171, v171
	v_mul_f32_e32 v138, v173, v173
	v_fmac_f32_e32 v136, v170, v170
	v_fmac_f32_e32 v138, v172, v172
	v_add_f32_e32 v136, v136, v138
	v_add_f32_e32 v136, v136, v137
	v_mov_b32_e32 v137, v136
	s_nop 1
	v_permlane16_swap_b32_e32 v136, v137
	v_add_f32_e32 v136, v136, v137
	v_mov_b32_e32 v137, v136
	s_nop 1
	v_permlane32_swap_b32_e32 v136, v137
	v_add_f32_e32 v136, v136, v137
	v_fmamk_f32 v136, v136, 0x3c800000, v191
	v_rsq_f32_e32 v174, v136
	s_nop 0
	v_pk_mul_f32 v[128:129], v[128:129], v[174:175] op_sel_hi:[1,0]
	v_pk_mul_f32 v[130:131], v[130:131], v[174:175] op_sel_hi:[1,0]
	v_pk_mul_f32 v[166:167], v[166:167], v[174:175] op_sel_hi:[1,0]
	v_pk_mul_f32 v[168:169], v[168:169], v[174:175] op_sel_hi:[1,0]
	v_pk_fma_f32 v[178:179], v[234:235], v[130:131], v[238:239]
	v_pk_fma_f32 v[182:183], v[232:233], v[128:129], v[236:237]
	v_pk_mul_f32 v[128:129], v[132:133], v[174:175] op_sel_hi:[1,0]
	v_pk_mul_f32 v[130:131], v[134:135], v[174:175] op_sel_hi:[1,0]
	v_pk_fma_f32 v[180:181], v[228:229], v[128:129], v[206:207]
	v_pk_fma_f32 v[176:177], v[230:231], v[130:131], v[208:209]
	s_nop 0
	v_pk_fma_f32 v[136:137], v[244:245], v[166:167], v[222:223]
	v_pk_mul_f32 v[140:141], v[170:171], v[174:175] op_sel_hi:[1,0]
	v_pk_fma_f32 v[138:139], v[246:247], v[168:169], v[224:225]
	v_pk_fma_f32 v[132:133], v[240:241], v[140:141], v[248:249]
	v_add_co_u32_e32 v140, vcc, s16, v156
	v_pk_mul_f32 v[142:143], v[172:173], v[174:175] op_sel_hi:[1,0]
	v_cvt_pk_bf16_f32 v128, v182, v183
	s_nop 0
	v_addc_co_u32_e32 v141, vcc, 0, v157, vcc
	v_pk_fma_f32 v[134:135], v[242:243], v[142:143], v[250:251]
	v_cvt_pk_bf16_f32 v129, v178, v179
	v_cvt_pk_bf16_f32 v130, v180, v181
	v_cvt_pk_bf16_f32 v131, v176, v177
	global_store_dwordx4 v[140:141], v[128:131], off
	s_mov_b32 s16, 0x20000
	s_nop 0
	v_cvt_pk_bf16_f32 v128, v136, v137
	v_mul_f32_e32 v136, v80, v80
	v_mul_f32_e32 v137, v81, v81
	v_fmamk_f32 v136, v136, 0xbdd2d3e7, v252
	v_fmamk_f32 v137, v137, 0xbdd2d3e7, v252
	v_mul_f32_e32 v136, v80, v136
	v_mul_f32_e32 v137, v81, v137
	v_exp_f32_e32 v136, v136
	v_exp_f32_e32 v137, v137
	v_cvt_pk_bf16_f32 v129, v138, v139
	v_cvt_pk_bf16_f32 v130, v132, v133
	v_add_f32_e32 v136, 1.0, v136
	v_add_f32_e32 v137, 1.0, v137
	v_rcp_f32_e32 v136, v136
	v_rcp_f32_e32 v137, v137
	v_cvt_pk_bf16_f32 v131, v134, v135
	global_store_dwordx4 v[140:141], v[128:131], off offset:64
	v_mul_f32_e32 v132, v92, v92
	v_pk_mul_f32 v[166:167], v[80:81], v[136:137]
	v_mul_f32_e32 v136, v82, v82
	v_mul_f32_e32 v137, v83, v83
	v_fmamk_f32 v136, v136, 0xbdd2d3e7, v252
	v_fmamk_f32 v137, v137, 0xbdd2d3e7, v252
	v_mul_f32_e32 v136, v82, v136
	v_mul_f32_e32 v137, v83, v137
	v_exp_f32_e32 v136, v136
	v_exp_f32_e32 v137, v137
	v_mul_f32_e32 v129, v101, v101
	v_mul_f32_e32 v130, v102, v102
	v_add_f32_e32 v136, 1.0, v136
	v_add_f32_e32 v137, 1.0, v137
	v_rcp_f32_e32 v136, v136
	v_rcp_f32_e32 v137, v137
	v_mul_f32_e32 v131, v103, v103
	v_fmamk_f32 v128, v159, 0xbdd2d3e7, v252
	v_fmamk_f32 v129, v129, 0xbdd2d3e7, v252
	v_pk_mul_f32 v[168:169], v[82:83], v[136:137]
	v_mul_f32_e32 v136, v72, v72
	v_mul_f32_e32 v137, v73, v73
	v_fmamk_f32 v136, v136, 0xbdd2d3e7, v252
	v_fmamk_f32 v137, v137, 0xbdd2d3e7, v252
	v_mul_f32_e32 v136, v72, v136
	v_mul_f32_e32 v137, v73, v137
	v_exp_f32_e32 v136, v136
	v_exp_f32_e32 v137, v137
	v_fmamk_f32 v130, v130, 0xbdd2d3e7, v252
	v_fmamk_f32 v131, v131, 0xbdd2d3e7, v252
	v_add_f32_e32 v136, 1.0, v136
	v_add_f32_e32 v137, 1.0, v137
	v_rcp_f32_e32 v136, v136
	v_rcp_f32_e32 v137, v137
	v_mul_f32_e32 v133, v93, v93
	v_mul_f32_e32 v134, v94, v94
	v_mul_f32_e32 v135, v95, v95
	v_pk_mul_f32 v[170:171], v[72:73], v[136:137]
	v_mul_f32_e32 v136, v74, v74
	v_mul_f32_e32 v137, v75, v75
	v_mul_f32_e32 v128, v100, v128
	v_mul_f32_e32 v129, v101, v129
	v_mul_f32_e32 v130, v102, v130
	v_mul_f32_e32 v131, v103, v131
	v_fmamk_f32 v132, v132, 0xbdd2d3e7, v252
	v_fmamk_f32 v133, v133, 0xbdd2d3e7, v252
	v_fmamk_f32 v134, v134, 0xbdd2d3e7, v252
	v_fmamk_f32 v135, v135, 0xbdd2d3e7, v252
	v_fmamk_f32 v136, v136, 0xbdd2d3e7, v252
	v_fmamk_f32 v137, v137, 0xbdd2d3e7, v252
	v_exp_f32_e32 v128, v128
	v_exp_f32_e32 v129, v129
	v_exp_f32_e32 v130, v130
	v_exp_f32_e32 v131, v131
	v_mul_f32_e32 v132, v92, v132
	v_mul_f32_e32 v133, v93, v133
	v_mul_f32_e32 v134, v94, v134
	v_mul_f32_e32 v135, v95, v135
	v_mul_f32_e32 v136, v74, v136
	v_mul_f32_e32 v137, v75, v137
	v_exp_f32_e32 v132, v132
	v_exp_f32_e32 v133, v133
	v_exp_f32_e32 v134, v134
	v_exp_f32_e32 v135, v135
	v_exp_f32_e32 v136, v136
	v_exp_f32_e32 v137, v137
	v_add_f32_e32 v128, 1.0, v128
	v_add_f32_e32 v129, 1.0, v129
	v_add_f32_e32 v130, 1.0, v130
	v_add_f32_e32 v131, 1.0, v131
	v_rcp_f32_e32 v128, v128
	v_rcp_f32_e32 v129, v129
	v_rcp_f32_e32 v130, v130
	v_rcp_f32_e32 v131, v131
	v_add_f32_e32 v132, 1.0, v132
	v_add_f32_e32 v133, 1.0, v133
	v_add_f32_e32 v134, 1.0, v134
	v_add_f32_e32 v135, 1.0, v135
	v_add_f32_e32 v136, 1.0, v136
	v_add_f32_e32 v137, 1.0, v137
	v_rcp_f32_e32 v132, v132
	v_rcp_f32_e32 v133, v133
	v_rcp_f32_e32 v134, v134
	v_rcp_f32_e32 v135, v135
	v_rcp_f32_e32 v136, v136
	v_rcp_f32_e32 v137, v137
	v_pk_mul_f32 v[128:129], v[100:101], v[128:129]
	v_pk_mul_f32 v[130:131], v[102:103], v[130:131]
	v_pk_mul_f32 v[132:133], v[92:93], v[132:133]
	v_pk_mul_f32 v[134:135], v[94:95], v[134:135]
	v_pk_mul_f32 v[172:173], v[74:75], v[136:137]
	v_add_f32_e32 v136, v130, v131
	v_add_f32_e32 v137, v128, v129
	v_add_f32_e32 v136, v137, v136
	v_add_f32_e32 v137, v134, v135
	v_add_f32_e32 v138, v132, v133
	v_add_f32_e32 v136, 0, v136
	v_add_f32_e32 v137, v138, v137
	v_add_f32_e32 v136, v136, v137
	v_add_f32_e32 v137, v168, v169
	v_add_f32_e32 v138, v166, v167
	v_add_f32_e32 v137, v138, v137
	v_add_f32_e32 v136, v136, v137
	v_add_f32_e32 v137, v172, v173
	v_add_f32_e32 v138, v170, v171
	v_add_f32_e32 v137, v138, v137
	v_add_f32_e32 v136, v136, v137
	v_mov_b32_e32 v137, v136
	s_nop 1
	v_permlane16_swap_b32_e32 v136, v137
	v_add_f32_e32 v136, v136, v137
	v_mov_b32_e32 v137, v136
	s_nop 1
	v_permlane32_swap_b32_e32 v136, v137
	v_add_f32_e32 v136, v136, v137
	v_fmac_f32_e32 v131, 0xbc800000, v136
	v_fmac_f32_e32 v129, 0xbc800000, v136
	v_fmamk_f32 v130, v136, 0xbc800000, v130
	v_fmamk_f32 v128, v136, 0xbc800000, v128
	v_mul_f32_e32 v137, v129, v129
	v_mul_f32_e32 v138, v131, v131
	v_fmac_f32_e32 v137, v128, v128
	v_fmac_f32_e32 v138, v130, v130
	v_fmac_f32_e32 v135, 0xbc800000, v136
	v_fmac_f32_e32 v133, 0xbc800000, v136
	v_add_f32_e32 v137, v137, v138
	v_fmamk_f32 v134, v136, 0xbc800000, v134
	v_fmamk_f32 v132, v136, 0xbc800000, v132
	v_mul_f32_e32 v138, v133, v133
	v_mul_f32_e32 v139, v135, v135
	v_fmac_f32_e32 v138, v132, v132
	v_fmac_f32_e32 v139, v134, v134
	v_add_f32_e32 v138, v138, v139
	v_fmac_f32_e32 v169, 0xbc800000, v136
	v_fmac_f32_e32 v167, 0xbc800000, v136
	v_add_f32_e32 v137, v137, v138
	v_fmamk_f32 v168, v136, 0xbc800000, v168
	v_fmamk_f32 v166, v136, 0xbc800000, v166
	v_mul_f32_e32 v138, v167, v167
	v_mul_f32_e32 v139, v169, v169
	v_fmac_f32_e32 v138, v166, v166
	v_fmac_f32_e32 v139, v168, v168
	v_add_f32_e32 v138, v138, v139
	v_fmac_f32_e32 v173, 0xbc800000, v136
	v_fmac_f32_e32 v171, 0xbc800000, v136
	v_add_f32_e32 v137, v138, v137
	v_fmamk_f32 v172, v136, 0xbc800000, v172
	v_fmamk_f32 v170, v136, 0xbc800000, v170
	v_mul_f32_e32 v136, v171, v171
	v_mul_f32_e32 v138, v173, v173
	v_fmac_f32_e32 v136, v170, v170
	v_fmac_f32_e32 v138, v172, v172
	v_add_f32_e32 v136, v136, v138
	v_add_f32_e32 v136, v136, v137
	v_mov_b32_e32 v137, v136
	s_nop 1
	v_permlane16_swap_b32_e32 v136, v137
	v_add_f32_e32 v136, v136, v137
	v_mov_b32_e32 v137, v136
	s_nop 1
	v_permlane32_swap_b32_e32 v136, v137
	v_add_f32_e32 v136, v136, v137
	v_fmamk_f32 v136, v136, 0x3c800000, v191
	v_rsq_f32_e32 v174, v136
	s_nop 0
	v_pk_mul_f32 v[128:129], v[128:129], v[174:175] op_sel_hi:[1,0]
	v_pk_mul_f32 v[130:131], v[130:131], v[174:175] op_sel_hi:[1,0]
	v_pk_mul_f32 v[166:167], v[166:167], v[174:175] op_sel_hi:[1,0]
	v_pk_mul_f32 v[168:169], v[168:169], v[174:175] op_sel_hi:[1,0]
	v_pk_fma_f32 v[178:179], v[234:235], v[130:131], v[238:239]
	v_pk_fma_f32 v[182:183], v[232:233], v[128:129], v[236:237]
	v_pk_mul_f32 v[128:129], v[132:133], v[174:175] op_sel_hi:[1,0]
	v_pk_mul_f32 v[130:131], v[134:135], v[174:175] op_sel_hi:[1,0]
	v_pk_fma_f32 v[180:181], v[228:229], v[128:129], v[206:207]
	v_pk_fma_f32 v[176:177], v[230:231], v[130:131], v[208:209]
	s_nop 0
	v_pk_fma_f32 v[136:137], v[244:245], v[166:167], v[222:223]
	v_pk_mul_f32 v[140:141], v[170:171], v[174:175] op_sel_hi:[1,0]
	v_pk_fma_f32 v[138:139], v[246:247], v[168:169], v[224:225]
	v_pk_fma_f32 v[132:133], v[240:241], v[140:141], v[248:249]
	v_add_co_u32_e32 v140, vcc, s16, v156
	v_pk_mul_f32 v[142:143], v[172:173], v[174:175] op_sel_hi:[1,0]
	v_cvt_pk_bf16_f32 v128, v182, v183
	s_nop 0
	v_addc_co_u32_e32 v141, vcc, 0, v157, vcc
	v_pk_fma_f32 v[134:135], v[242:243], v[142:143], v[250:251]
	v_cvt_pk_bf16_f32 v129, v178, v179
	v_cvt_pk_bf16_f32 v130, v180, v181
	v_cvt_pk_bf16_f32 v131, v176, v177
	global_store_dwordx4 v[140:141], v[128:131], off
	s_mov_b32 s16, 0x30000
	s_nop 0
	v_cvt_pk_bf16_f32 v128, v136, v137
	v_mul_f32_e32 v136, v68, v68
	v_mul_f32_e32 v137, v69, v69
	v_fmamk_f32 v136, v136, 0xbdd2d3e7, v252
	v_fmamk_f32 v137, v137, 0xbdd2d3e7, v252
	v_mul_f32_e32 v136, v68, v136
	v_mul_f32_e32 v137, v69, v137
	v_exp_f32_e32 v136, v136
	v_exp_f32_e32 v137, v137
	v_cvt_pk_bf16_f32 v129, v138, v139
	v_cvt_pk_bf16_f32 v130, v132, v133
	v_add_f32_e32 v136, 1.0, v136
	v_add_f32_e32 v137, 1.0, v137
	v_rcp_f32_e32 v136, v136
	v_rcp_f32_e32 v137, v137
	v_cvt_pk_bf16_f32 v131, v134, v135
	global_store_dwordx4 v[140:141], v[128:131], off offset:64
	v_mul_f32_e32 v132, v76, v76
	v_pk_mul_f32 v[166:167], v[68:69], v[136:137]
	v_mul_f32_e32 v136, v70, v70
	v_mul_f32_e32 v137, v71, v71
	v_fmamk_f32 v136, v136, 0xbdd2d3e7, v252
	v_fmamk_f32 v137, v137, 0xbdd2d3e7, v252
	v_mul_f32_e32 v136, v70, v136
	v_mul_f32_e32 v137, v71, v137
	v_exp_f32_e32 v136, v136
	v_exp_f32_e32 v137, v137
	v_mul_f32_e32 v128, v84, v84
	v_mul_f32_e32 v129, v85, v85
	v_add_f32_e32 v136, 1.0, v136
	v_add_f32_e32 v137, 1.0, v137
	v_rcp_f32_e32 v136, v136
	v_rcp_f32_e32 v137, v137
	v_mul_f32_e32 v130, v86, v86
	v_mul_f32_e32 v131, v87, v87
	v_fmamk_f32 v128, v128, 0xbdd2d3e7, v252
	v_pk_mul_f32 v[168:169], v[70:71], v[136:137]
	v_mul_f32_e32 v136, v64, v64
	v_mul_f32_e32 v137, v65, v65
	v_fmamk_f32 v136, v136, 0xbdd2d3e7, v252
	v_fmamk_f32 v137, v137, 0xbdd2d3e7, v252
	v_mul_f32_e32 v136, v64, v136
	v_mul_f32_e32 v137, v65, v137
	v_exp_f32_e32 v136, v136
	v_exp_f32_e32 v137, v137
	v_fmamk_f32 v129, v129, 0xbdd2d3e7, v252
	v_fmamk_f32 v130, v130, 0xbdd2d3e7, v252
	v_add_f32_e32 v136, 1.0, v136
	v_add_f32_e32 v137, 1.0, v137
	v_rcp_f32_e32 v136, v136
	v_rcp_f32_e32 v137, v137
	v_fmamk_f32 v131, v131, 0xbdd2d3e7, v252
	v_mul_f32_e32 v133, v77, v77
	v_mul_f32_e32 v134, v78, v78
	v_mul_f32_e32 v135, v79, v79
	v_pk_mul_f32 v[170:171], v[64:65], v[136:137]
	v_mul_f32_e32 v136, v66, v66
	v_mul_f32_e32 v137, v67, v67
	v_mul_f32_e32 v128, v84, v128
	v_mul_f32_e32 v129, v85, v129
	v_mul_f32_e32 v130, v86, v130
	v_mul_f32_e32 v131, v87, v131
	v_fmamk_f32 v132, v132, 0xbdd2d3e7, v252
	v_fmamk_f32 v133, v133, 0xbdd2d3e7, v252
	v_fmamk_f32 v134, v134, 0xbdd2d3e7, v252
	v_fmamk_f32 v135, v135, 0xbdd2d3e7, v252
	v_fmamk_f32 v136, v136, 0xbdd2d3e7, v252
	v_fmamk_f32 v137, v137, 0xbdd2d3e7, v252
	v_exp_f32_e32 v128, v128
	v_exp_f32_e32 v129, v129
	v_exp_f32_e32 v130, v130
	v_exp_f32_e32 v131, v131
	v_mul_f32_e32 v132, v76, v132
	v_mul_f32_e32 v133, v77, v133
	v_mul_f32_e32 v134, v78, v134
	v_mul_f32_e32 v135, v79, v135
	v_mul_f32_e32 v136, v66, v136
	v_mul_f32_e32 v137, v67, v137
	v_exp_f32_e32 v132, v132
	v_exp_f32_e32 v133, v133
	v_exp_f32_e32 v134, v134
	v_exp_f32_e32 v135, v135
	v_exp_f32_e32 v136, v136
	v_exp_f32_e32 v137, v137
	v_add_f32_e32 v128, 1.0, v128
	v_add_f32_e32 v129, 1.0, v129
	v_add_f32_e32 v130, 1.0, v130
	v_add_f32_e32 v131, 1.0, v131
	v_rcp_f32_e32 v128, v128
	v_rcp_f32_e32 v129, v129
	v_rcp_f32_e32 v130, v130
	v_rcp_f32_e32 v131, v131
	v_add_f32_e32 v132, 1.0, v132
	v_add_f32_e32 v133, 1.0, v133
	v_add_f32_e32 v134, 1.0, v134
	v_add_f32_e32 v135, 1.0, v135
	v_add_f32_e32 v136, 1.0, v136
	v_add_f32_e32 v137, 1.0, v137
	v_rcp_f32_e32 v132, v132
	v_rcp_f32_e32 v133, v133
	v_rcp_f32_e32 v134, v134
	v_rcp_f32_e32 v135, v135
	v_rcp_f32_e32 v136, v136
	v_rcp_f32_e32 v137, v137
	v_pk_mul_f32 v[128:129], v[84:85], v[128:129]
	v_pk_mul_f32 v[130:131], v[86:87], v[130:131]
	v_pk_mul_f32 v[132:133], v[76:77], v[132:133]
	v_pk_mul_f32 v[134:135], v[78:79], v[134:135]
	v_pk_mul_f32 v[172:173], v[66:67], v[136:137]
	v_add_f32_e32 v136, v130, v131
	v_add_f32_e32 v137, v128, v129
	v_add_f32_e32 v136, v137, v136
	v_add_f32_e32 v137, v134, v135
	v_add_f32_e32 v138, v132, v133
	v_add_f32_e32 v136, 0, v136
	v_add_f32_e32 v137, v138, v137
	v_add_f32_e32 v136, v136, v137
	v_add_f32_e32 v137, v168, v169
	v_add_f32_e32 v138, v166, v167
	v_add_f32_e32 v137, v138, v137
	v_add_f32_e32 v136, v136, v137
	v_add_f32_e32 v137, v172, v173
	v_add_f32_e32 v138, v170, v171
	v_add_f32_e32 v137, v138, v137
	v_add_f32_e32 v136, v136, v137
	v_mov_b32_e32 v137, v136
	s_nop 1
	v_permlane16_swap_b32_e32 v136, v137
	v_add_f32_e32 v136, v136, v137
	v_mov_b32_e32 v137, v136
	s_nop 1
	v_permlane32_swap_b32_e32 v136, v137
	v_add_f32_e32 v136, v136, v137
	v_fmac_f32_e32 v131, 0xbc800000, v136
	v_fmac_f32_e32 v129, 0xbc800000, v136
	v_fmamk_f32 v130, v136, 0xbc800000, v130
	v_fmamk_f32 v128, v136, 0xbc800000, v128
	v_mul_f32_e32 v137, v129, v129
	v_mul_f32_e32 v138, v131, v131
	v_fmac_f32_e32 v137, v128, v128
	v_fmac_f32_e32 v138, v130, v130
	v_fmac_f32_e32 v135, 0xbc800000, v136
	v_fmac_f32_e32 v133, 0xbc800000, v136
	v_add_f32_e32 v137, v137, v138
	v_fmamk_f32 v134, v136, 0xbc800000, v134
	v_fmamk_f32 v132, v136, 0xbc800000, v132
	v_mul_f32_e32 v138, v133, v133
	v_mul_f32_e32 v139, v135, v135
	v_fmac_f32_e32 v138, v132, v132
	v_fmac_f32_e32 v139, v134, v134
	v_add_f32_e32 v138, v138, v139
	v_fmac_f32_e32 v169, 0xbc800000, v136
	v_fmac_f32_e32 v167, 0xbc800000, v136
	v_add_f32_e32 v137, v137, v138
	v_fmamk_f32 v168, v136, 0xbc800000, v168
	v_fmamk_f32 v166, v136, 0xbc800000, v166
	v_mul_f32_e32 v138, v167, v167
	v_mul_f32_e32 v139, v169, v169
	v_fmac_f32_e32 v138, v166, v166
	v_fmac_f32_e32 v139, v168, v168
	v_add_f32_e32 v138, v138, v139
	v_fmac_f32_e32 v173, 0xbc800000, v136
	v_fmac_f32_e32 v171, 0xbc800000, v136
	v_add_f32_e32 v137, v138, v137
	v_fmamk_f32 v172, v136, 0xbc800000, v172
	v_fmamk_f32 v170, v136, 0xbc800000, v170
	v_mul_f32_e32 v136, v171, v171
	v_mul_f32_e32 v138, v173, v173
	v_fmac_f32_e32 v136, v170, v170
	v_fmac_f32_e32 v138, v172, v172
	v_add_f32_e32 v136, v136, v138
	v_add_f32_e32 v136, v136, v137
	v_mov_b32_e32 v137, v136
	s_nop 1
	v_permlane16_swap_b32_e32 v136, v137
	v_add_f32_e32 v136, v136, v137
	v_mov_b32_e32 v137, v136
	s_nop 1
	v_permlane32_swap_b32_e32 v136, v137
	v_add_f32_e32 v136, v136, v137
	v_fmamk_f32 v136, v136, 0x3c800000, v191
	v_rsq_f32_e32 v174, v136
	s_nop 0
	v_pk_mul_f32 v[128:129], v[128:129], v[174:175] op_sel_hi:[1,0]
	v_pk_mul_f32 v[130:131], v[130:131], v[174:175] op_sel_hi:[1,0]
	v_pk_mul_f32 v[166:167], v[166:167], v[174:175] op_sel_hi:[1,0]
	v_pk_mul_f32 v[168:169], v[168:169], v[174:175] op_sel_hi:[1,0]
	v_pk_fma_f32 v[178:179], v[234:235], v[130:131], v[238:239]
	v_pk_fma_f32 v[182:183], v[232:233], v[128:129], v[236:237]
	v_pk_mul_f32 v[128:129], v[132:133], v[174:175] op_sel_hi:[1,0]
	v_pk_mul_f32 v[130:131], v[134:135], v[174:175] op_sel_hi:[1,0]
	v_pk_fma_f32 v[180:181], v[228:229], v[128:129], v[206:207]
	v_pk_fma_f32 v[176:177], v[230:231], v[130:131], v[208:209]
	s_nop 0
	v_pk_fma_f32 v[136:137], v[244:245], v[166:167], v[222:223]
	v_pk_mul_f32 v[140:141], v[170:171], v[174:175] op_sel_hi:[1,0]
	v_pk_fma_f32 v[138:139], v[246:247], v[168:169], v[224:225]
	v_pk_fma_f32 v[132:133], v[240:241], v[140:141], v[248:249]
	v_add_co_u32_e32 v140, vcc, s16, v156
	v_pk_mul_f32 v[142:143], v[172:173], v[174:175] op_sel_hi:[1,0]
	v_cvt_pk_bf16_f32 v128, v182, v183
	s_nop 0
	v_addc_co_u32_e32 v141, vcc, 0, v157, vcc
	v_pk_fma_f32 v[134:135], v[242:243], v[142:143], v[250:251]
	v_cvt_pk_bf16_f32 v129, v178, v179
	v_cvt_pk_bf16_f32 v130, v180, v181
	v_cvt_pk_bf16_f32 v131, v176, v177
	global_store_dwordx4 v[140:141], v[128:131], off
	s_mov_b32 s16, 0x80000
	s_nop 0
	v_cvt_pk_bf16_f32 v128, v136, v137
	v_mul_f32_e32 v136, v48, v48
	v_mul_f32_e32 v137, v49, v49
	v_fmamk_f32 v136, v136, 0xbdd2d3e7, v252
	v_fmamk_f32 v137, v137, 0xbdd2d3e7, v252
	v_mul_f32_e32 v136, v48, v136
	v_mul_f32_e32 v137, v49, v137
	v_exp_f32_e32 v136, v136
	v_exp_f32_e32 v137, v137
	v_cvt_pk_bf16_f32 v129, v138, v139
	v_cvt_pk_bf16_f32 v130, v132, v133
	v_add_f32_e32 v136, 1.0, v136
	v_add_f32_e32 v137, 1.0, v137
	v_rcp_f32_e32 v136, v136
	v_rcp_f32_e32 v137, v137
	v_cvt_pk_bf16_f32 v131, v134, v135
	global_store_dwordx4 v[140:141], v[128:131], off offset:64
	v_mul_f32_e32 v132, v56, v56
	v_pk_mul_f32 v[166:167], v[48:49], v[136:137]
	v_mul_f32_e32 v136, v50, v50
	v_mul_f32_e32 v137, v51, v51
	v_fmamk_f32 v136, v136, 0xbdd2d3e7, v252
	v_fmamk_f32 v137, v137, 0xbdd2d3e7, v252
	v_mul_f32_e32 v136, v50, v136
	v_mul_f32_e32 v137, v51, v137
	v_exp_f32_e32 v136, v136
	v_exp_f32_e32 v137, v137
	v_mul_f32_e32 v128, v60, v60
	v_mul_f32_e32 v129, v61, v61
	v_add_f32_e32 v136, 1.0, v136
	v_add_f32_e32 v137, 1.0, v137
	v_rcp_f32_e32 v136, v136
	v_rcp_f32_e32 v137, v137
	v_mul_f32_e32 v130, v62, v62
	v_mul_f32_e32 v131, v63, v63
	v_fmamk_f32 v128, v128, 0xbdd2d3e7, v252
	v_pk_mul_f32 v[168:169], v[50:51], v[136:137]
	v_mul_f32_e32 v136, v40, v40
	v_mul_f32_e32 v137, v41, v41
	v_fmamk_f32 v136, v136, 0xbdd2d3e7, v252
	v_fmamk_f32 v137, v137, 0xbdd2d3e7, v252
	v_mul_f32_e32 v136, v40, v136
	v_mul_f32_e32 v137, v41, v137
	v_exp_f32_e32 v136, v136
	v_exp_f32_e32 v137, v137
	v_fmamk_f32 v129, v129, 0xbdd2d3e7, v252
	v_fmamk_f32 v130, v130, 0xbdd2d3e7, v252
	v_add_f32_e32 v136, 1.0, v136
	v_add_f32_e32 v137, 1.0, v137
	v_rcp_f32_e32 v136, v136
	v_rcp_f32_e32 v137, v137
	v_fmamk_f32 v131, v131, 0xbdd2d3e7, v252
	v_mul_f32_e32 v133, v57, v57
	v_mul_f32_e32 v134, v58, v58
	v_mul_f32_e32 v135, v59, v59
	v_pk_mul_f32 v[170:171], v[40:41], v[136:137]
	v_mul_f32_e32 v136, v42, v42
	v_mul_f32_e32 v137, v43, v43
	v_mul_f32_e32 v128, v60, v128
	v_mul_f32_e32 v129, v61, v129
	v_mul_f32_e32 v130, v62, v130
	v_mul_f32_e32 v131, v63, v131
	v_fmamk_f32 v132, v132, 0xbdd2d3e7, v252
	v_fmamk_f32 v133, v133, 0xbdd2d3e7, v252
	v_fmamk_f32 v134, v134, 0xbdd2d3e7, v252
	v_fmamk_f32 v135, v135, 0xbdd2d3e7, v252
	v_fmamk_f32 v136, v136, 0xbdd2d3e7, v252
	v_fmamk_f32 v137, v137, 0xbdd2d3e7, v252
	v_exp_f32_e32 v128, v128
	v_exp_f32_e32 v129, v129
	v_exp_f32_e32 v130, v130
	v_exp_f32_e32 v131, v131
	v_mul_f32_e32 v132, v56, v132
	v_mul_f32_e32 v133, v57, v133
	v_mul_f32_e32 v134, v58, v134
	v_mul_f32_e32 v135, v59, v135
	v_mul_f32_e32 v136, v42, v136
	v_mul_f32_e32 v137, v43, v137
	v_exp_f32_e32 v132, v132
	v_exp_f32_e32 v133, v133
	v_exp_f32_e32 v134, v134
	v_exp_f32_e32 v135, v135
	v_exp_f32_e32 v136, v136
	v_exp_f32_e32 v137, v137
	v_add_f32_e32 v128, 1.0, v128
	v_add_f32_e32 v129, 1.0, v129
	v_add_f32_e32 v130, 1.0, v130
	v_add_f32_e32 v131, 1.0, v131
	v_rcp_f32_e32 v128, v128
	v_rcp_f32_e32 v129, v129
	v_rcp_f32_e32 v130, v130
	v_rcp_f32_e32 v131, v131
	v_add_f32_e32 v132, 1.0, v132
	v_add_f32_e32 v133, 1.0, v133
	v_add_f32_e32 v134, 1.0, v134
	v_add_f32_e32 v135, 1.0, v135
	v_add_f32_e32 v136, 1.0, v136
	v_add_f32_e32 v137, 1.0, v137
	v_rcp_f32_e32 v132, v132
	v_rcp_f32_e32 v133, v133
	v_rcp_f32_e32 v134, v134
	v_rcp_f32_e32 v135, v135
	v_rcp_f32_e32 v136, v136
	v_rcp_f32_e32 v137, v137
	v_pk_mul_f32 v[128:129], v[60:61], v[128:129]
	v_pk_mul_f32 v[130:131], v[62:63], v[130:131]
	v_pk_mul_f32 v[132:133], v[56:57], v[132:133]
	v_pk_mul_f32 v[134:135], v[58:59], v[134:135]
	v_pk_mul_f32 v[172:173], v[42:43], v[136:137]
	v_add_f32_e32 v136, v130, v131
	v_add_f32_e32 v137, v128, v129
	v_add_f32_e32 v136, v137, v136
	v_add_f32_e32 v137, v134, v135
	v_add_f32_e32 v138, v132, v133
	v_add_f32_e32 v136, 0, v136
	v_add_f32_e32 v137, v138, v137
	v_add_f32_e32 v136, v136, v137
	v_add_f32_e32 v137, v168, v169
	v_add_f32_e32 v138, v166, v167
	v_add_f32_e32 v137, v138, v137
	v_add_f32_e32 v136, v136, v137
	v_add_f32_e32 v137, v172, v173
	v_add_f32_e32 v138, v170, v171
	v_add_f32_e32 v137, v138, v137
	v_add_f32_e32 v136, v136, v137
	v_mov_b32_e32 v137, v136
	s_nop 1
	v_permlane16_swap_b32_e32 v136, v137
	v_add_f32_e32 v136, v136, v137
	v_mov_b32_e32 v137, v136
	s_nop 1
	v_permlane32_swap_b32_e32 v136, v137
	v_add_f32_e32 v136, v136, v137
	v_fmac_f32_e32 v131, 0xbc800000, v136
	v_fmac_f32_e32 v129, 0xbc800000, v136
	v_fmamk_f32 v130, v136, 0xbc800000, v130
	v_fmamk_f32 v128, v136, 0xbc800000, v128
	v_mul_f32_e32 v137, v129, v129
	v_mul_f32_e32 v138, v131, v131
	v_fmac_f32_e32 v137, v128, v128
	v_fmac_f32_e32 v138, v130, v130
	v_fmac_f32_e32 v135, 0xbc800000, v136
	v_fmac_f32_e32 v133, 0xbc800000, v136
	v_add_f32_e32 v137, v137, v138
	v_fmamk_f32 v134, v136, 0xbc800000, v134
	v_fmamk_f32 v132, v136, 0xbc800000, v132
	v_mul_f32_e32 v138, v133, v133
	v_mul_f32_e32 v139, v135, v135
	v_fmac_f32_e32 v138, v132, v132
	v_fmac_f32_e32 v139, v134, v134
	v_add_f32_e32 v138, v138, v139
	v_fmac_f32_e32 v169, 0xbc800000, v136
	v_fmac_f32_e32 v167, 0xbc800000, v136
	v_add_f32_e32 v137, v137, v138
	v_fmamk_f32 v168, v136, 0xbc800000, v168
	v_fmamk_f32 v166, v136, 0xbc800000, v166
	v_mul_f32_e32 v138, v167, v167
	v_mul_f32_e32 v139, v169, v169
	v_fmac_f32_e32 v138, v166, v166
	v_fmac_f32_e32 v139, v168, v168
	v_add_f32_e32 v138, v138, v139
	v_fmac_f32_e32 v173, 0xbc800000, v136
	v_fmac_f32_e32 v171, 0xbc800000, v136
	v_add_f32_e32 v137, v138, v137
	v_fmamk_f32 v172, v136, 0xbc800000, v172
	v_fmamk_f32 v170, v136, 0xbc800000, v170
	v_mul_f32_e32 v136, v171, v171
	v_mul_f32_e32 v138, v173, v173
	v_fmac_f32_e32 v136, v170, v170
	v_fmac_f32_e32 v138, v172, v172
	v_add_f32_e32 v136, v136, v138
	v_add_f32_e32 v136, v136, v137
	v_mov_b32_e32 v137, v136
	s_nop 1
	v_permlane16_swap_b32_e32 v136, v137
	v_add_f32_e32 v136, v136, v137
	v_mov_b32_e32 v137, v136
	s_nop 1
	v_permlane32_swap_b32_e32 v136, v137
	v_add_f32_e32 v136, v136, v137
	v_fmamk_f32 v136, v136, 0x3c800000, v191
	v_rsq_f32_e32 v174, v136
	s_nop 0
	v_pk_mul_f32 v[128:129], v[128:129], v[174:175] op_sel_hi:[1,0]
	v_pk_mul_f32 v[130:131], v[130:131], v[174:175] op_sel_hi:[1,0]
	v_pk_mul_f32 v[166:167], v[166:167], v[174:175] op_sel_hi:[1,0]
	v_pk_mul_f32 v[168:169], v[168:169], v[174:175] op_sel_hi:[1,0]
	v_pk_fma_f32 v[178:179], v[234:235], v[130:131], v[238:239]
	v_pk_fma_f32 v[182:183], v[232:233], v[128:129], v[236:237]
	v_pk_mul_f32 v[128:129], v[132:133], v[174:175] op_sel_hi:[1,0]
	v_pk_mul_f32 v[130:131], v[134:135], v[174:175] op_sel_hi:[1,0]
	v_pk_fma_f32 v[180:181], v[228:229], v[128:129], v[206:207]
	v_pk_fma_f32 v[176:177], v[230:231], v[130:131], v[208:209]
	s_nop 0
	v_pk_fma_f32 v[136:137], v[244:245], v[166:167], v[222:223]
	v_pk_mul_f32 v[140:141], v[170:171], v[174:175] op_sel_hi:[1,0]
	v_pk_fma_f32 v[138:139], v[246:247], v[168:169], v[224:225]
	v_pk_fma_f32 v[132:133], v[240:241], v[140:141], v[248:249]
	v_add_co_u32_e32 v140, vcc, s16, v156
	v_pk_mul_f32 v[142:143], v[172:173], v[174:175] op_sel_hi:[1,0]
	v_cvt_pk_bf16_f32 v128, v182, v183
	s_nop 0
	v_addc_co_u32_e32 v141, vcc, 0, v157, vcc
	v_pk_fma_f32 v[134:135], v[242:243], v[142:143], v[250:251]
	v_cvt_pk_bf16_f32 v129, v178, v179
	v_cvt_pk_bf16_f32 v130, v180, v181
	v_cvt_pk_bf16_f32 v131, v176, v177
	global_store_dwordx4 v[140:141], v[128:131], off
	s_mov_b32 s16, 0x90000
	s_nop 0
	v_cvt_pk_bf16_f32 v128, v136, v137
	v_mul_f32_e32 v136, v32, v32
	v_mul_f32_e32 v137, v33, v33
	v_fmamk_f32 v136, v136, 0xbdd2d3e7, v252
	v_fmamk_f32 v137, v137, 0xbdd2d3e7, v252
	v_mul_f32_e32 v136, v32, v136
	v_mul_f32_e32 v137, v33, v137
	v_exp_f32_e32 v136, v136
	v_exp_f32_e32 v137, v137
	v_cvt_pk_bf16_f32 v129, v138, v139
	v_cvt_pk_bf16_f32 v130, v132, v133
	v_add_f32_e32 v136, 1.0, v136
	v_add_f32_e32 v137, 1.0, v137
	v_rcp_f32_e32 v136, v136
	v_rcp_f32_e32 v137, v137
	v_cvt_pk_bf16_f32 v131, v134, v135
	global_store_dwordx4 v[140:141], v[128:131], off offset:64
	v_mul_f32_e32 v132, v44, v44
	v_pk_mul_f32 v[166:167], v[32:33], v[136:137]
	v_mul_f32_e32 v136, v34, v34
	v_mul_f32_e32 v137, v35, v35
	v_fmamk_f32 v136, v136, 0xbdd2d3e7, v252
	v_fmamk_f32 v137, v137, 0xbdd2d3e7, v252
	v_mul_f32_e32 v136, v34, v136
	v_mul_f32_e32 v137, v35, v137
	v_exp_f32_e32 v136, v136
	v_exp_f32_e32 v137, v137
	v_mul_f32_e32 v128, v52, v52
	v_mul_f32_e32 v129, v53, v53
	v_add_f32_e32 v136, 1.0, v136
	v_add_f32_e32 v137, 1.0, v137
	v_rcp_f32_e32 v136, v136
	v_rcp_f32_e32 v137, v137
	v_mul_f32_e32 v130, v54, v54
	v_mul_f32_e32 v131, v55, v55
	v_fmamk_f32 v128, v128, 0xbdd2d3e7, v252
	v_pk_mul_f32 v[168:169], v[34:35], v[136:137]
	v_mul_f32_e32 v136, v24, v24
	v_mul_f32_e32 v137, v25, v25
	v_fmamk_f32 v136, v136, 0xbdd2d3e7, v252
	v_fmamk_f32 v137, v137, 0xbdd2d3e7, v252
	v_mul_f32_e32 v136, v24, v136
	v_mul_f32_e32 v137, v25, v137
	v_exp_f32_e32 v136, v136
	v_exp_f32_e32 v137, v137
	v_fmamk_f32 v129, v129, 0xbdd2d3e7, v252
	v_fmamk_f32 v130, v130, 0xbdd2d3e7, v252
	v_add_f32_e32 v136, 1.0, v136
	v_add_f32_e32 v137, 1.0, v137
	v_rcp_f32_e32 v136, v136
	v_rcp_f32_e32 v137, v137
	v_fmamk_f32 v131, v131, 0xbdd2d3e7, v252
	v_mul_f32_e32 v133, v45, v45
	v_mul_f32_e32 v134, v46, v46
	v_mul_f32_e32 v135, v47, v47
	v_pk_mul_f32 v[170:171], v[24:25], v[136:137]
	v_mul_f32_e32 v136, v26, v26
	v_mul_f32_e32 v137, v27, v27
	v_mul_f32_e32 v128, v52, v128
	v_mul_f32_e32 v129, v53, v129
	v_mul_f32_e32 v130, v54, v130
	v_mul_f32_e32 v131, v55, v131
	v_fmamk_f32 v132, v132, 0xbdd2d3e7, v252
	v_fmamk_f32 v133, v133, 0xbdd2d3e7, v252
	v_fmamk_f32 v134, v134, 0xbdd2d3e7, v252
	v_fmamk_f32 v135, v135, 0xbdd2d3e7, v252
	v_fmamk_f32 v136, v136, 0xbdd2d3e7, v252
	v_fmamk_f32 v137, v137, 0xbdd2d3e7, v252
	v_exp_f32_e32 v128, v128
	v_exp_f32_e32 v129, v129
	v_exp_f32_e32 v130, v130
	v_exp_f32_e32 v131, v131
	v_mul_f32_e32 v132, v44, v132
	v_mul_f32_e32 v133, v45, v133
	v_mul_f32_e32 v134, v46, v134
	v_mul_f32_e32 v135, v47, v135
	v_mul_f32_e32 v136, v26, v136
	v_mul_f32_e32 v137, v27, v137
	v_exp_f32_e32 v132, v132
	v_exp_f32_e32 v133, v133
	v_exp_f32_e32 v134, v134
	v_exp_f32_e32 v135, v135
	v_exp_f32_e32 v136, v136
	v_exp_f32_e32 v137, v137
	v_add_f32_e32 v128, 1.0, v128
	v_add_f32_e32 v129, 1.0, v129
	v_add_f32_e32 v130, 1.0, v130
	v_add_f32_e32 v131, 1.0, v131
	v_rcp_f32_e32 v128, v128
	v_rcp_f32_e32 v129, v129
	v_rcp_f32_e32 v130, v130
	v_rcp_f32_e32 v131, v131
	v_add_f32_e32 v132, 1.0, v132
	v_add_f32_e32 v133, 1.0, v133
	v_add_f32_e32 v134, 1.0, v134
	v_add_f32_e32 v135, 1.0, v135
	v_add_f32_e32 v136, 1.0, v136
	v_add_f32_e32 v137, 1.0, v137
	v_rcp_f32_e32 v132, v132
	v_rcp_f32_e32 v133, v133
	v_rcp_f32_e32 v134, v134
	v_rcp_f32_e32 v135, v135
	v_rcp_f32_e32 v136, v136
	v_rcp_f32_e32 v137, v137
	v_pk_mul_f32 v[128:129], v[52:53], v[128:129]
	v_pk_mul_f32 v[130:131], v[54:55], v[130:131]
	v_pk_mul_f32 v[132:133], v[44:45], v[132:133]
	v_pk_mul_f32 v[134:135], v[46:47], v[134:135]
	v_pk_mul_f32 v[172:173], v[26:27], v[136:137]
	v_add_f32_e32 v136, v130, v131
	v_add_f32_e32 v137, v128, v129
	v_add_f32_e32 v136, v137, v136
	v_add_f32_e32 v137, v134, v135
	v_add_f32_e32 v138, v132, v133
	v_add_f32_e32 v136, 0, v136
	v_add_f32_e32 v137, v138, v137
	v_add_f32_e32 v136, v136, v137
	v_add_f32_e32 v137, v168, v169
	v_add_f32_e32 v138, v166, v167
	v_add_f32_e32 v137, v138, v137
	v_add_f32_e32 v136, v136, v137
	v_add_f32_e32 v137, v172, v173
	v_add_f32_e32 v138, v170, v171
	v_add_f32_e32 v137, v138, v137
	v_add_f32_e32 v136, v136, v137
	v_mov_b32_e32 v137, v136
	s_nop 1
	v_permlane16_swap_b32_e32 v136, v137
	v_add_f32_e32 v136, v136, v137
	v_mov_b32_e32 v137, v136
	s_nop 1
	v_permlane32_swap_b32_e32 v136, v137
	v_add_f32_e32 v136, v136, v137
	v_fmac_f32_e32 v131, 0xbc800000, v136
	v_fmac_f32_e32 v129, 0xbc800000, v136
	v_fmamk_f32 v130, v136, 0xbc800000, v130
	v_fmamk_f32 v128, v136, 0xbc800000, v128
	v_mul_f32_e32 v137, v129, v129
	v_mul_f32_e32 v138, v131, v131
	v_fmac_f32_e32 v137, v128, v128
	v_fmac_f32_e32 v138, v130, v130
	v_fmac_f32_e32 v135, 0xbc800000, v136
	v_fmac_f32_e32 v133, 0xbc800000, v136
	v_add_f32_e32 v137, v137, v138
	v_fmamk_f32 v134, v136, 0xbc800000, v134
	v_fmamk_f32 v132, v136, 0xbc800000, v132
	v_mul_f32_e32 v138, v133, v133
	v_mul_f32_e32 v139, v135, v135
	v_fmac_f32_e32 v138, v132, v132
	v_fmac_f32_e32 v139, v134, v134
	v_add_f32_e32 v138, v138, v139
	v_fmac_f32_e32 v169, 0xbc800000, v136
	v_fmac_f32_e32 v167, 0xbc800000, v136
	v_add_f32_e32 v137, v137, v138
	v_fmamk_f32 v168, v136, 0xbc800000, v168
	v_fmamk_f32 v166, v136, 0xbc800000, v166
	v_mul_f32_e32 v138, v167, v167
	v_mul_f32_e32 v139, v169, v169
	v_fmac_f32_e32 v138, v166, v166
	v_fmac_f32_e32 v139, v168, v168
	v_add_f32_e32 v138, v138, v139
	v_fmac_f32_e32 v173, 0xbc800000, v136
	v_fmac_f32_e32 v171, 0xbc800000, v136
	v_add_f32_e32 v137, v138, v137
	v_fmamk_f32 v172, v136, 0xbc800000, v172
	v_fmamk_f32 v170, v136, 0xbc800000, v170
	v_mul_f32_e32 v136, v171, v171
	v_mul_f32_e32 v138, v173, v173
	v_fmac_f32_e32 v136, v170, v170
	v_fmac_f32_e32 v138, v172, v172
	v_add_f32_e32 v136, v136, v138
	v_add_f32_e32 v136, v136, v137
	v_mov_b32_e32 v137, v136
	s_nop 1
	v_permlane16_swap_b32_e32 v136, v137
	v_add_f32_e32 v136, v136, v137
	v_mov_b32_e32 v137, v136
	s_nop 1
	v_permlane32_swap_b32_e32 v136, v137
	v_add_f32_e32 v136, v136, v137
	v_fmamk_f32 v136, v136, 0x3c800000, v191
	v_rsq_f32_e32 v174, v136
	s_nop 0
	v_pk_mul_f32 v[128:129], v[128:129], v[174:175] op_sel_hi:[1,0]
	v_pk_mul_f32 v[130:131], v[130:131], v[174:175] op_sel_hi:[1,0]
	v_pk_mul_f32 v[166:167], v[166:167], v[174:175] op_sel_hi:[1,0]
	v_pk_mul_f32 v[168:169], v[168:169], v[174:175] op_sel_hi:[1,0]
	v_pk_fma_f32 v[178:179], v[234:235], v[130:131], v[238:239]
	v_pk_fma_f32 v[182:183], v[232:233], v[128:129], v[236:237]
	v_pk_mul_f32 v[128:129], v[132:133], v[174:175] op_sel_hi:[1,0]
	v_pk_mul_f32 v[130:131], v[134:135], v[174:175] op_sel_hi:[1,0]
	v_pk_fma_f32 v[180:181], v[228:229], v[128:129], v[206:207]
	v_pk_fma_f32 v[176:177], v[230:231], v[130:131], v[208:209]
	s_nop 0
	v_pk_fma_f32 v[136:137], v[244:245], v[166:167], v[222:223]
	v_pk_mul_f32 v[140:141], v[170:171], v[174:175] op_sel_hi:[1,0]
	v_pk_fma_f32 v[138:139], v[246:247], v[168:169], v[224:225]
	v_pk_fma_f32 v[132:133], v[240:241], v[140:141], v[248:249]
	v_add_co_u32_e32 v140, vcc, s16, v156
	v_pk_mul_f32 v[142:143], v[172:173], v[174:175] op_sel_hi:[1,0]
	v_cvt_pk_bf16_f32 v128, v182, v183
	s_nop 0
	v_addc_co_u32_e32 v141, vcc, 0, v157, vcc
	v_pk_fma_f32 v[134:135], v[242:243], v[142:143], v[250:251]
	v_cvt_pk_bf16_f32 v129, v178, v179
	v_cvt_pk_bf16_f32 v130, v180, v181
	v_cvt_pk_bf16_f32 v131, v176, v177
	global_store_dwordx4 v[140:141], v[128:131], off
	s_mov_b32 s16, 0xa0000
	s_nop 0
	v_cvt_pk_bf16_f32 v128, v136, v137
	v_mul_f32_e32 v136, v16, v16
	v_mul_f32_e32 v137, v17, v17
	v_fmamk_f32 v136, v136, 0xbdd2d3e7, v252
	v_fmamk_f32 v137, v137, 0xbdd2d3e7, v252
	v_mul_f32_e32 v136, v16, v136
	v_mul_f32_e32 v137, v17, v137
	v_exp_f32_e32 v136, v136
	v_exp_f32_e32 v137, v137
	v_cvt_pk_bf16_f32 v129, v138, v139
	v_cvt_pk_bf16_f32 v130, v132, v133
	v_add_f32_e32 v136, 1.0, v136
	v_add_f32_e32 v137, 1.0, v137
	v_rcp_f32_e32 v136, v136
	v_rcp_f32_e32 v137, v137
	v_cvt_pk_bf16_f32 v131, v134, v135
	global_store_dwordx4 v[140:141], v[128:131], off offset:64
	v_mul_f32_e32 v132, v28, v28
	v_pk_mul_f32 v[166:167], v[16:17], v[136:137]
	v_mul_f32_e32 v136, v18, v18
	v_mul_f32_e32 v137, v19, v19
	v_fmamk_f32 v136, v136, 0xbdd2d3e7, v252
	v_fmamk_f32 v137, v137, 0xbdd2d3e7, v252
	v_mul_f32_e32 v136, v18, v136
	v_mul_f32_e32 v137, v19, v137
	v_exp_f32_e32 v136, v136
	v_exp_f32_e32 v137, v137
	v_mul_f32_e32 v128, v36, v36
	v_mul_f32_e32 v129, v37, v37
	v_add_f32_e32 v136, 1.0, v136
	v_add_f32_e32 v137, 1.0, v137
	v_rcp_f32_e32 v136, v136
	v_rcp_f32_e32 v137, v137
	v_mul_f32_e32 v130, v38, v38
	v_mul_f32_e32 v131, v39, v39
	v_fmamk_f32 v128, v128, 0xbdd2d3e7, v252
	v_pk_mul_f32 v[168:169], v[18:19], v[136:137]
	v_mul_f32_e32 v136, v8, v8
	v_mul_f32_e32 v137, v9, v9
	v_fmamk_f32 v136, v136, 0xbdd2d3e7, v252
	v_fmamk_f32 v137, v137, 0xbdd2d3e7, v252
	v_mul_f32_e32 v136, v8, v136
	v_mul_f32_e32 v137, v9, v137
	v_exp_f32_e32 v136, v136
	v_exp_f32_e32 v137, v137
	v_fmamk_f32 v129, v129, 0xbdd2d3e7, v252
	v_fmamk_f32 v130, v130, 0xbdd2d3e7, v252
	v_add_f32_e32 v136, 1.0, v136
	v_add_f32_e32 v137, 1.0, v137
	v_rcp_f32_e32 v136, v136
	v_rcp_f32_e32 v137, v137
	v_fmamk_f32 v131, v131, 0xbdd2d3e7, v252
	v_mul_f32_e32 v133, v29, v29
	v_mul_f32_e32 v134, v30, v30
	v_mul_f32_e32 v135, v31, v31
	v_pk_mul_f32 v[170:171], v[8:9], v[136:137]
	v_mul_f32_e32 v136, v10, v10
	v_mul_f32_e32 v137, v11, v11
	v_mul_f32_e32 v128, v36, v128
	v_mul_f32_e32 v129, v37, v129
	v_mul_f32_e32 v130, v38, v130
	v_mul_f32_e32 v131, v39, v131
	v_fmamk_f32 v132, v132, 0xbdd2d3e7, v252
	v_fmamk_f32 v133, v133, 0xbdd2d3e7, v252
	v_fmamk_f32 v134, v134, 0xbdd2d3e7, v252
	v_fmamk_f32 v135, v135, 0xbdd2d3e7, v252
	v_fmamk_f32 v136, v136, 0xbdd2d3e7, v252
	v_fmamk_f32 v137, v137, 0xbdd2d3e7, v252
	v_exp_f32_e32 v128, v128
	v_exp_f32_e32 v129, v129
	v_exp_f32_e32 v130, v130
	v_exp_f32_e32 v131, v131
	v_mul_f32_e32 v132, v28, v132
	v_mul_f32_e32 v133, v29, v133
	v_mul_f32_e32 v134, v30, v134
	v_mul_f32_e32 v135, v31, v135
	v_mul_f32_e32 v136, v10, v136
	v_mul_f32_e32 v137, v11, v137
	v_exp_f32_e32 v132, v132
	v_exp_f32_e32 v133, v133
	v_exp_f32_e32 v134, v134
	v_exp_f32_e32 v135, v135
	v_exp_f32_e32 v136, v136
	v_exp_f32_e32 v137, v137
	v_add_f32_e32 v128, 1.0, v128
	v_add_f32_e32 v129, 1.0, v129
	v_add_f32_e32 v130, 1.0, v130
	v_add_f32_e32 v131, 1.0, v131
	v_rcp_f32_e32 v128, v128
	v_rcp_f32_e32 v129, v129
	v_rcp_f32_e32 v130, v130
	v_rcp_f32_e32 v131, v131
	v_add_f32_e32 v132, 1.0, v132
	v_add_f32_e32 v133, 1.0, v133
	v_add_f32_e32 v134, 1.0, v134
	v_add_f32_e32 v135, 1.0, v135
	v_add_f32_e32 v136, 1.0, v136
	v_add_f32_e32 v137, 1.0, v137
	v_rcp_f32_e32 v132, v132
	v_rcp_f32_e32 v133, v133
	v_rcp_f32_e32 v134, v134
	v_rcp_f32_e32 v135, v135
	v_rcp_f32_e32 v136, v136
	v_rcp_f32_e32 v137, v137
	v_pk_mul_f32 v[128:129], v[36:37], v[128:129]
	v_pk_mul_f32 v[130:131], v[38:39], v[130:131]
	v_pk_mul_f32 v[132:133], v[28:29], v[132:133]
	v_pk_mul_f32 v[134:135], v[30:31], v[134:135]
	v_pk_mul_f32 v[172:173], v[10:11], v[136:137]
	v_add_f32_e32 v136, v130, v131
	v_add_f32_e32 v137, v128, v129
	v_add_f32_e32 v136, v137, v136
	v_add_f32_e32 v137, v134, v135
	v_add_f32_e32 v138, v132, v133
	v_add_f32_e32 v136, 0, v136
	v_add_f32_e32 v137, v138, v137
	v_add_f32_e32 v136, v136, v137
	v_add_f32_e32 v137, v168, v169
	v_add_f32_e32 v138, v166, v167
	v_add_f32_e32 v137, v138, v137
	v_add_f32_e32 v136, v136, v137
	v_add_f32_e32 v137, v172, v173
	v_add_f32_e32 v138, v170, v171
	v_add_f32_e32 v137, v138, v137
	v_add_f32_e32 v136, v136, v137
	v_mov_b32_e32 v137, v136
	s_nop 1
	v_permlane16_swap_b32_e32 v136, v137
	v_add_f32_e32 v136, v136, v137
	v_mov_b32_e32 v137, v136
	s_nop 1
	v_permlane32_swap_b32_e32 v136, v137
	v_add_f32_e32 v136, v136, v137
	v_fmac_f32_e32 v131, 0xbc800000, v136
	v_fmac_f32_e32 v129, 0xbc800000, v136
	v_fmamk_f32 v130, v136, 0xbc800000, v130
	v_fmamk_f32 v128, v136, 0xbc800000, v128
	v_mul_f32_e32 v137, v129, v129
	v_mul_f32_e32 v138, v131, v131
	v_fmac_f32_e32 v137, v128, v128
	v_fmac_f32_e32 v138, v130, v130
	v_fmac_f32_e32 v135, 0xbc800000, v136
	v_fmac_f32_e32 v133, 0xbc800000, v136
	v_add_f32_e32 v137, v137, v138
	v_fmamk_f32 v134, v136, 0xbc800000, v134
	v_fmamk_f32 v132, v136, 0xbc800000, v132
	v_mul_f32_e32 v138, v133, v133
	v_mul_f32_e32 v139, v135, v135
	v_fmac_f32_e32 v138, v132, v132
	v_fmac_f32_e32 v139, v134, v134
	v_add_f32_e32 v138, v138, v139
	v_fmac_f32_e32 v169, 0xbc800000, v136
	v_fmac_f32_e32 v167, 0xbc800000, v136
	v_add_f32_e32 v137, v137, v138
	v_fmamk_f32 v168, v136, 0xbc800000, v168
	v_fmamk_f32 v166, v136, 0xbc800000, v166
	v_mul_f32_e32 v138, v167, v167
	v_mul_f32_e32 v139, v169, v169
	v_fmac_f32_e32 v138, v166, v166
	v_fmac_f32_e32 v139, v168, v168
	v_add_f32_e32 v138, v138, v139
	v_fmac_f32_e32 v173, 0xbc800000, v136
	v_fmac_f32_e32 v171, 0xbc800000, v136
	v_add_f32_e32 v137, v138, v137
	v_fmamk_f32 v172, v136, 0xbc800000, v172
	v_fmamk_f32 v170, v136, 0xbc800000, v170
	v_mul_f32_e32 v136, v171, v171
	v_mul_f32_e32 v138, v173, v173
	v_fmac_f32_e32 v136, v170, v170
	v_fmac_f32_e32 v138, v172, v172
	v_add_f32_e32 v136, v136, v138
	v_add_f32_e32 v136, v136, v137
	v_mov_b32_e32 v137, v136
	s_nop 1
	v_permlane16_swap_b32_e32 v136, v137
	v_add_f32_e32 v136, v136, v137
	v_mov_b32_e32 v137, v136
	s_nop 1
	v_permlane32_swap_b32_e32 v136, v137
	v_add_f32_e32 v136, v136, v137
	v_fmamk_f32 v136, v136, 0x3c800000, v191
	v_rsq_f32_e32 v174, v136
	s_nop 0
	v_pk_mul_f32 v[128:129], v[128:129], v[174:175] op_sel_hi:[1,0]
	v_pk_mul_f32 v[130:131], v[130:131], v[174:175] op_sel_hi:[1,0]
	v_pk_mul_f32 v[166:167], v[166:167], v[174:175] op_sel_hi:[1,0]
	v_pk_mul_f32 v[168:169], v[168:169], v[174:175] op_sel_hi:[1,0]
	v_pk_fma_f32 v[178:179], v[234:235], v[130:131], v[238:239]
	v_pk_fma_f32 v[182:183], v[232:233], v[128:129], v[236:237]
	v_pk_mul_f32 v[128:129], v[132:133], v[174:175] op_sel_hi:[1,0]
	v_pk_mul_f32 v[130:131], v[134:135], v[174:175] op_sel_hi:[1,0]
	v_pk_fma_f32 v[180:181], v[228:229], v[128:129], v[206:207]
	v_pk_fma_f32 v[176:177], v[230:231], v[130:131], v[208:209]
	s_nop 0
	v_pk_fma_f32 v[136:137], v[244:245], v[166:167], v[222:223]
	v_pk_mul_f32 v[140:141], v[170:171], v[174:175] op_sel_hi:[1,0]
	v_pk_fma_f32 v[138:139], v[246:247], v[168:169], v[224:225]
	v_pk_fma_f32 v[132:133], v[240:241], v[140:141], v[248:249]
	v_add_co_u32_e32 v140, vcc, s16, v156
	v_pk_mul_f32 v[142:143], v[172:173], v[174:175] op_sel_hi:[1,0]
	v_cvt_pk_bf16_f32 v128, v182, v183
	s_nop 0
	v_addc_co_u32_e32 v141, vcc, 0, v157, vcc
	v_pk_fma_f32 v[134:135], v[242:243], v[142:143], v[250:251]
	v_cvt_pk_bf16_f32 v129, v178, v179
	v_cvt_pk_bf16_f32 v130, v180, v181
	v_cvt_pk_bf16_f32 v131, v176, v177
	global_store_dwordx4 v[140:141], v[128:131], off
	s_mov_b32 s16, 0xb0000
	s_nop 0
	v_cvt_pk_bf16_f32 v128, v136, v137
	v_mul_f32_e32 v136, v4, v4
	v_mul_f32_e32 v137, v5, v5
	v_fmamk_f32 v136, v136, 0xbdd2d3e7, v252
	v_fmamk_f32 v137, v137, 0xbdd2d3e7, v252
	v_mul_f32_e32 v136, v4, v136
	v_mul_f32_e32 v137, v5, v137
	v_exp_f32_e32 v136, v136
	v_exp_f32_e32 v137, v137
	v_cvt_pk_bf16_f32 v129, v138, v139
	v_cvt_pk_bf16_f32 v130, v132, v133
	v_add_f32_e32 v136, 1.0, v136
	v_add_f32_e32 v137, 1.0, v137
	v_rcp_f32_e32 v136, v136
	v_rcp_f32_e32 v137, v137
	v_cvt_pk_bf16_f32 v131, v134, v135
	global_store_dwordx4 v[140:141], v[128:131], off offset:64
	v_mul_f32_e32 v132, v12, v12
	v_pk_mul_f32 v[166:167], v[4:5], v[136:137]
	v_mul_f32_e32 v136, v6, v6
	v_mul_f32_e32 v137, v7, v7
	v_fmamk_f32 v136, v136, 0xbdd2d3e7, v252
	v_fmamk_f32 v137, v137, 0xbdd2d3e7, v252
	v_mul_f32_e32 v136, v6, v136
	v_mul_f32_e32 v137, v7, v137
	v_exp_f32_e32 v136, v136
	v_exp_f32_e32 v137, v137
	v_mul_f32_e32 v128, v20, v20
	v_mul_f32_e32 v129, v21, v21
	v_add_f32_e32 v136, 1.0, v136
	v_add_f32_e32 v137, 1.0, v137
	v_rcp_f32_e32 v136, v136
	v_rcp_f32_e32 v137, v137
	v_mul_f32_e32 v130, v22, v22
	v_mul_f32_e32 v131, v23, v23
	v_fmamk_f32 v128, v128, 0xbdd2d3e7, v252
	v_pk_mul_f32 v[168:169], v[6:7], v[136:137]
	v_mul_f32_e32 v136, v0, v0
	v_mul_f32_e32 v137, v1, v1
	v_fmamk_f32 v136, v136, 0xbdd2d3e7, v252
	v_fmamk_f32 v137, v137, 0xbdd2d3e7, v252
	v_mul_f32_e32 v136, v0, v136
	v_mul_f32_e32 v137, v1, v137
	v_exp_f32_e32 v136, v136
	v_exp_f32_e32 v137, v137
	v_fmamk_f32 v129, v129, 0xbdd2d3e7, v252
	v_fmamk_f32 v130, v130, 0xbdd2d3e7, v252
	v_add_f32_e32 v136, 1.0, v136
	v_add_f32_e32 v137, 1.0, v137
	v_rcp_f32_e32 v136, v136
	v_rcp_f32_e32 v137, v137
	v_fmamk_f32 v131, v131, 0xbdd2d3e7, v252
	v_mul_f32_e32 v133, v13, v13
	v_mul_f32_e32 v134, v14, v14
	v_mul_f32_e32 v135, v15, v15
	v_pk_mul_f32 v[170:171], v[0:1], v[136:137]
	v_mul_f32_e32 v136, v2, v2
	v_mul_f32_e32 v137, v3, v3
	v_mul_f32_e32 v128, v20, v128
	v_mul_f32_e32 v129, v21, v129
	v_mul_f32_e32 v130, v22, v130
	v_mul_f32_e32 v131, v23, v131
	v_fmamk_f32 v132, v132, 0xbdd2d3e7, v252
	v_fmamk_f32 v133, v133, 0xbdd2d3e7, v252
	v_fmamk_f32 v134, v134, 0xbdd2d3e7, v252
	v_fmamk_f32 v135, v135, 0xbdd2d3e7, v252
	v_fmamk_f32 v136, v136, 0xbdd2d3e7, v252
	v_fmamk_f32 v137, v137, 0xbdd2d3e7, v252
	v_exp_f32_e32 v128, v128
	v_exp_f32_e32 v129, v129
	v_exp_f32_e32 v130, v130
	v_exp_f32_e32 v131, v131
	v_mul_f32_e32 v132, v12, v132
	v_mul_f32_e32 v133, v13, v133
	v_mul_f32_e32 v134, v14, v134
	v_mul_f32_e32 v135, v15, v135
	v_mul_f32_e32 v136, v2, v136
	v_mul_f32_e32 v137, v3, v137
	v_exp_f32_e32 v132, v132
	v_exp_f32_e32 v133, v133
	v_exp_f32_e32 v134, v134
	v_exp_f32_e32 v135, v135
	v_exp_f32_e32 v136, v136
	v_exp_f32_e32 v137, v137
	v_add_f32_e32 v128, 1.0, v128
	v_add_f32_e32 v129, 1.0, v129
	v_add_f32_e32 v130, 1.0, v130
	v_add_f32_e32 v131, 1.0, v131
	v_rcp_f32_e32 v128, v128
	v_rcp_f32_e32 v129, v129
	v_rcp_f32_e32 v130, v130
	v_rcp_f32_e32 v131, v131
	v_add_f32_e32 v132, 1.0, v132
	v_add_f32_e32 v133, 1.0, v133
	v_add_f32_e32 v134, 1.0, v134
	v_add_f32_e32 v135, 1.0, v135
	v_add_f32_e32 v136, 1.0, v136
	v_add_f32_e32 v137, 1.0, v137
	v_rcp_f32_e32 v132, v132
	v_rcp_f32_e32 v133, v133
	v_rcp_f32_e32 v134, v134
	v_rcp_f32_e32 v135, v135
	v_rcp_f32_e32 v136, v136
	v_rcp_f32_e32 v137, v137
	v_pk_mul_f32 v[128:129], v[20:21], v[128:129]
	v_pk_mul_f32 v[130:131], v[22:23], v[130:131]
	v_pk_mul_f32 v[132:133], v[12:13], v[132:133]
	v_pk_mul_f32 v[134:135], v[14:15], v[134:135]
	v_pk_mul_f32 v[172:173], v[2:3], v[136:137]
	v_add_f32_e32 v136, v130, v131
	v_add_f32_e32 v137, v128, v129
	v_add_f32_e32 v136, v137, v136
	v_add_f32_e32 v137, v134, v135
	v_add_f32_e32 v138, v132, v133
	v_add_f32_e32 v136, 0, v136
	v_add_f32_e32 v137, v138, v137
	v_add_f32_e32 v136, v136, v137
	v_add_f32_e32 v137, v168, v169
	v_add_f32_e32 v138, v166, v167
	v_add_f32_e32 v137, v138, v137
	v_add_f32_e32 v136, v136, v137
	v_add_f32_e32 v137, v172, v173
	v_add_f32_e32 v138, v170, v171
	v_add_f32_e32 v137, v138, v137
	v_add_f32_e32 v136, v136, v137
	v_mov_b32_e32 v137, v136
	s_nop 1
	v_permlane16_swap_b32_e32 v136, v137
	v_add_f32_e32 v136, v136, v137
	v_mov_b32_e32 v137, v136
	s_nop 1
	v_permlane32_swap_b32_e32 v136, v137
	v_add_f32_e32 v136, v136, v137
	v_fmac_f32_e32 v131, 0xbc800000, v136
	v_fmac_f32_e32 v129, 0xbc800000, v136
	v_fmamk_f32 v130, v136, 0xbc800000, v130
	v_fmamk_f32 v128, v136, 0xbc800000, v128
	v_mul_f32_e32 v137, v129, v129
	v_mul_f32_e32 v138, v131, v131
	v_fmac_f32_e32 v137, v128, v128
	v_fmac_f32_e32 v138, v130, v130
	v_fmac_f32_e32 v135, 0xbc800000, v136
	v_fmac_f32_e32 v133, 0xbc800000, v136
	v_add_f32_e32 v137, v137, v138
	v_fmamk_f32 v134, v136, 0xbc800000, v134
	v_fmamk_f32 v132, v136, 0xbc800000, v132
	v_mul_f32_e32 v138, v133, v133
	v_mul_f32_e32 v139, v135, v135
	v_fmac_f32_e32 v138, v132, v132
	v_fmac_f32_e32 v139, v134, v134
	v_add_f32_e32 v138, v138, v139
	v_fmac_f32_e32 v169, 0xbc800000, v136
	v_fmac_f32_e32 v167, 0xbc800000, v136
	v_add_f32_e32 v137, v137, v138
	v_fmamk_f32 v168, v136, 0xbc800000, v168
	v_fmamk_f32 v166, v136, 0xbc800000, v166
	v_mul_f32_e32 v138, v167, v167
	v_mul_f32_e32 v139, v169, v169
	v_fmac_f32_e32 v138, v166, v166
	v_fmac_f32_e32 v139, v168, v168
	v_add_f32_e32 v138, v138, v139
	v_fmac_f32_e32 v173, 0xbc800000, v136
	v_fmac_f32_e32 v171, 0xbc800000, v136
	v_add_f32_e32 v137, v138, v137
	v_fmamk_f32 v172, v136, 0xbc800000, v172
	v_fmamk_f32 v170, v136, 0xbc800000, v170
	v_mul_f32_e32 v136, v171, v171
	v_mul_f32_e32 v138, v173, v173
	v_fmac_f32_e32 v136, v170, v170
	v_fmac_f32_e32 v138, v172, v172
	v_add_f32_e32 v136, v136, v138
	v_add_f32_e32 v136, v136, v137
	v_mov_b32_e32 v137, v136
	s_nop 1
	v_permlane16_swap_b32_e32 v136, v137
	v_add_f32_e32 v136, v136, v137
	v_mov_b32_e32 v137, v136
	s_nop 1
	v_permlane32_swap_b32_e32 v136, v137
	v_add_f32_e32 v136, v136, v137
	v_fmamk_f32 v136, v136, 0x3c800000, v191
	v_rsq_f32_e32 v174, v136
	s_nop 0
	v_pk_mul_f32 v[128:129], v[128:129], v[174:175] op_sel_hi:[1,0]
	v_pk_mul_f32 v[130:131], v[130:131], v[174:175] op_sel_hi:[1,0]
	v_pk_fma_f32 v[182:183], v[232:233], v[128:129], v[236:237]
	v_pk_fma_f32 v[178:179], v[234:235], v[130:131], v[238:239]
	v_pk_mul_f32 v[128:129], v[132:133], v[174:175] op_sel_hi:[1,0]
	v_pk_mul_f32 v[130:131], v[134:135], v[174:175] op_sel_hi:[1,0]
	v_pk_fma_f32 v[180:181], v[228:229], v[128:129], v[206:207]
	v_pk_fma_f32 v[176:177], v[230:231], v[130:131], v[208:209]
	s_nop 0
	v_pk_mul_f32 v[162:163], v[166:167], v[174:175] op_sel_hi:[1,0]
	v_pk_mul_f32 v[164:165], v[168:169], v[174:175] op_sel_hi:[1,0]
	v_pk_fma_f32 v[136:137], v[244:245], v[162:163], v[222:223]
	v_pk_mul_f32 v[140:141], v[170:171], v[174:175] op_sel_hi:[1,0]
	v_pk_fma_f32 v[138:139], v[246:247], v[164:165], v[224:225]
	v_pk_mul_f32 v[142:143], v[172:173], v[174:175] op_sel_hi:[1,0]
	v_pk_fma_f32 v[132:133], v[240:241], v[140:141], v[248:249]
	v_add_co_u32_e32 v140, vcc, s16, v156
	v_pk_fma_f32 v[134:135], v[242:243], v[142:143], v[250:251]
	v_cvt_pk_bf16_f32 v128, v182, v183
	v_cvt_pk_bf16_f32 v129, v178, v179
	v_cvt_pk_bf16_f32 v130, v180, v181
	v_cvt_pk_bf16_f32 v131, v176, v177
	s_nop 0
	v_addc_co_u32_e32 v141, vcc, 0, v157, vcc
	global_store_dwordx4 v[140:141], v[128:131], off
	s_mov_b64 s[16:17], 0
	s_nop 0
	v_cvt_pk_bf16_f32 v128, v136, v137
	v_cvt_pk_bf16_f32 v129, v138, v139
	v_cvt_pk_bf16_f32 v130, v132, v133
	v_cvt_pk_bf16_f32 v131, v134, v135

.LBB0_145:
	s_andn2_b64 vcc, exec, s[16:17]
	s_cbranch_vccnz .LBB0_147
	v_lshl_add_u64 v[220:221], v[160:161], 2, s[44:45]
	global_load_dwordx4 v[194:197], v[220:221], off offset:16
	global_load_dwordx4 v[198:201], v[220:221], off
	global_load_dwordx4 v[202:205], v[220:221], off offset:144
	global_load_dwordx4 v[206:209], v[220:221], off offset:128
	v_lshlrev_b32_e32 v224, 2, v187
	v_ashrrev_i32_e32 v225, 31, v224
	v_lshlrev_b32_e32 v226, 5, v158
	v_mov_b32_e32 v223, 0
	v_and_b32_e32 v222, 0x1ffe0, v226
	v_lshl_add_u64 v[182:183], v[222:223], 0, v[224:225]
	v_lshl_add_u64 v[182:183], v[182:183], 3, s[40:41]
	global_load_dwordx4 v[228:231], v[182:183], off offset:16
	global_load_dwordx4 v[232:235], v[182:183], off
	v_or_b32_e32 v222, 16, v222
	v_lshl_add_u64 v[182:183], v[222:223], 0, v[224:225]
	v_lshl_add_u64 v[182:183], v[182:183], 3, s[40:41]
	global_load_dwordx4 v[236:239], v[182:183], off offset:16
	global_load_dwordx4 v[240:243], v[182:183], off
	v_add_u32_e32 v222, 0x200, v226
	v_and_b32_e32 v222, 0x1ffe0, v222
	v_lshl_add_u64 v[182:183], v[222:223], 0, v[224:225]
	v_lshl_add_u64 v[182:183], v[182:183], 3, s[40:41]
	global_load_dwordx4 v[244:247], v[182:183], off offset:16
	global_load_dwordx4 v[248:251], v[182:183], off
	v_or_b32_e32 v222, 16, v222
	v_lshl_add_u64 v[182:183], v[222:223], 0, v[224:225]
	v_lshl_add_u64 v[182:183], v[182:183], 3, s[40:41]
	global_load_dwordx4 v[178:181], v[182:183], off offset:16
	global_load_dwordx4 v[210:213], v[182:183], off
	v_mul_f32_e32 v128, v125, v125
	v_mul_f32_e32 v129, v127, v127
	v_fmac_f32_e32 v128, v124, v124
	v_fmac_f32_e32 v129, v126, v126
	v_add_f32_e32 v128, v128, v129
	v_mul_f32_e32 v129, v121, v121
	v_mul_f32_e32 v130, v123, v123
	v_fmac_f32_e32 v129, v120, v120
	v_fmac_f32_e32 v130, v122, v122
	v_add_f32_e32 v129, v129, v130
	v_add_f32_e32 v128, v128, v129
	v_mul_f32_e32 v129, v113, v113
	v_mul_f32_e32 v130, v115, v115
	v_fmac_f32_e32 v129, v112, v112
	v_fmac_f32_e32 v130, v114, v114
	v_add_f32_e32 v129, v129, v130
	v_add_f32_e32 v128, v128, v129
	v_mul_f32_e32 v129, v105, v105
	v_mul_f32_e32 v130, v107, v107
	v_fmac_f32_e32 v129, v104, v104
	v_fmac_f32_e32 v130, v106, v106
	v_add_f32_e32 v129, v129, v130
	v_add_f32_e32 v128, v128, v129
	v_mov_b32_e32 v129, v128
	s_nop 1
	v_permlane16_swap_b32_e32 v128, v129
	v_add_f32_e32 v128, v128, v129
	v_mov_b32_e32 v129, v128
	s_nop 1
	v_permlane32_swap_b32_e32 v128, v129
	v_add_f32_e32 v128, v128, v129
	v_mov_b32_e32 v177, 0x358637bd
	v_fmamk_f32 v128, v128, 0x3c800000, v177
	v_rsq_f32_e32 v128, v128
	v_lshlrev_b32_e32 v142, 2, v187
	v_lshlrev_b32_e32 v159, 5, v158
	v_ashrrev_i32_e32 v143, 31, v142
	v_and_b32_e32 v188, 0x1ffe0, v159
	v_lshl_add_u64 v[140:141], v[160:161], 2, s[44:45]
	v_lshl_add_u64 v[136:137], v[188:189], 0, v[142:143]
	v_mul_f32_e32 v160, s70, v128
	v_lshl_add_u64 v[162:163], v[136:137], 3, s[40:41]
	s_nop 0
	v_pk_mul_f32 v[166:167], v[124:125], v[160:161] op_sel_hi:[1,0]
	v_pk_mul_f32 v[168:169], v[126:127], v[160:161] op_sel_hi:[1,0]
	v_or_b32_e32 v188, 16, v188
	s_mov_b32 s16, 0x10000
	s_waitcnt vmcnt(4)
	v_pk_mul_f32 v[132:133], v[198:199], v[166:167]
	v_pk_mul_f32 v[134:135], v[200:201], v[168:169]
	v_pk_mul_f32 v[168:169], v[232:233], v[132:133]
	v_pk_mul_f32 v[132:133], v[232:233], v[132:133] op_sel:[1,0] op_sel_hi:[0,1]
	v_add_f32_e32 v161, v132, v133
	v_pk_mul_f32 v[132:133], v[234:235], v[134:135] op_sel:[1,0] op_sel_hi:[0,1]
	v_pk_mul_f32 v[166:167], v[234:235], v[134:135]
	v_add_f32_e32 v171, v132, v133
	v_pk_mul_f32 v[132:133], v[120:121], v[160:161] op_sel_hi:[1,0]
	v_pk_mul_f32 v[134:135], v[122:123], v[160:161] op_sel_hi:[1,0]
	v_pk_mul_f32 v[128:129], v[194:195], v[132:133]
	v_pk_mul_f32 v[130:131], v[196:197], v[134:135]
	v_pk_mul_f32 v[134:135], v[228:229], v[128:129]
	v_pk_mul_f32 v[132:133], v[230:231], v[130:131]
	v_pk_mul_f32 v[128:129], v[228:229], v[128:129] op_sel:[1,0] op_sel_hi:[0,1]
	v_add_f32_e32 v173, v128, v129
	v_sub_f32_e32 v174, v132, v133
	v_pk_mul_f32 v[128:129], v[230:231], v[130:131] op_sel:[1,0] op_sel_hi:[0,1]
	v_lshl_add_u64 v[132:133], v[188:189], 0, v[142:143]
	v_add_f32_e32 v176, v128, v129
	v_lshl_add_u64 v[136:137], v[132:133], 3, s[40:41]
	v_sub_f32_e32 v172, v134, v135
	s_nop 0
	v_sub_f32_e32 v170, v166, v167
	v_pk_mul_f32 v[166:167], v[112:113], v[160:161] op_sel_hi:[1,0]
	v_sub_f32_e32 v158, v168, v169
	v_pk_mul_f32 v[168:169], v[114:115], v[160:161] op_sel_hi:[1,0]
	v_pk_mul_f32 v[162:163], v[206:207], v[166:167]
	v_pk_mul_f32 v[164:165], v[208:209], v[168:169]
	v_pk_mul_f32 v[168:169], v[240:241], v[162:163]
	v_pk_mul_f32 v[136:137], v[240:241], v[162:163] op_sel:[1,0] op_sel_hi:[0,1]
	v_add_f32_e32 v162, v136, v137
	v_pk_mul_f32 v[136:137], v[242:243], v[164:165] op_sel:[1,0] op_sel_hi:[0,1]
	v_pk_mul_f32 v[166:167], v[242:243], v[164:165]
	v_add_f32_e32 v164, v136, v137
	v_pk_mul_f32 v[136:137], v[104:105], v[160:161] op_sel_hi:[1,0]
	v_pk_mul_f32 v[138:139], v[106:107], v[160:161] op_sel_hi:[1,0]
	v_pk_mul_f32 v[128:129], v[202:203], v[136:137]
	v_pk_mul_f32 v[130:131], v[204:205], v[138:139]
	v_pk_mul_f32 v[138:139], v[236:237], v[128:129]
	v_pk_mul_f32 v[128:129], v[236:237], v[128:129] op_sel:[1,0] op_sel_hi:[0,1]
	v_add_f32_e32 v132, v128, v129
	v_pk_mul_f32 v[128:129], v[238:239], v[130:131] op_sel:[1,0] op_sel_hi:[0,1]
	v_pk_mul_f32 v[136:137], v[238:239], v[130:131]
	v_add_f32_e32 v134, v128, v129
	v_cvt_pk_bf16_f32 v128, v158, v161
	v_cvt_pk_bf16_f32 v129, v170, v171
	v_sub_f32_e32 v168, v168, v169
	v_sub_f32_e32 v163, v166, v167
	v_cvt_pk_bf16_f32 v130, v172, v173
	v_cvt_pk_bf16_f32 v131, v174, v176
	global_store_dwordx4 v[156:157], v[128:131], off
	v_sub_f32_e32 v138, v138, v139
	v_sub_f32_e32 v133, v136, v137
	v_cvt_pk_bf16_f32 v128, v168, v162
	v_cvt_pk_bf16_f32 v129, v163, v164
	v_cvt_pk_bf16_f32 v130, v138, v132
	v_cvt_pk_bf16_f32 v131, v133, v134
	global_store_dwordx4 v[156:157], v[128:131], off offset:64
	s_nop 1
	v_add_u32_e32 v222, 0x400, v226
	v_and_b32_e32 v222, 0x1ffe0, v222
	v_lshl_add_u64 v[182:183], v[222:223], 0, v[224:225]
	v_lshl_add_u64 v[182:183], v[182:183], 3, s[40:41]
	global_load_dwordx4 v[228:231], v[182:183], off offset:16
	global_load_dwordx4 v[232:235], v[182:183], off
	v_or_b32_e32 v222, 16, v222
	v_lshl_add_u64 v[182:183], v[222:223], 0, v[224:225]
	v_lshl_add_u64 v[182:183], v[182:183], 3, s[40:41]
	global_load_dwordx4 v[236:239], v[182:183], off offset:16
	global_load_dwordx4 v[240:243], v[182:183], off
	v_mul_f32_e32 v128, v117, v117
	v_mul_f32_e32 v129, v119, v119
	v_fmac_f32_e32 v128, v116, v116
	v_fmac_f32_e32 v129, v118, v118
	v_add_f32_e32 v128, v128, v129
	v_mul_f32_e32 v129, v109, v109
	v_mul_f32_e32 v130, v111, v111
	v_fmac_f32_e32 v129, v108, v108
	v_fmac_f32_e32 v130, v110, v110
	v_add_f32_e32 v129, v129, v130
	v_add_f32_e32 v128, v128, v129
	v_mul_f32_e32 v129, v97, v97
	v_mul_f32_e32 v130, v99, v99
	v_fmac_f32_e32 v129, v96, v96
	v_fmac_f32_e32 v130, v98, v98
	v_add_f32_e32 v129, v129, v130
	v_add_f32_e32 v128, v128, v129
	v_mul_f32_e32 v129, v89, v89
	v_mul_f32_e32 v130, v91, v91
	v_fmac_f32_e32 v129, v88, v88
	v_fmac_f32_e32 v130, v90, v90
	v_add_f32_e32 v129, v129, v130
	v_add_f32_e32 v128, v128, v129
	v_mov_b32_e32 v129, v128
	s_nop 1
	v_permlane16_swap_b32_e32 v128, v129
	v_add_f32_e32 v128, v128, v129
	v_mov_b32_e32 v129, v128
	s_nop 1
	v_permlane32_swap_b32_e32 v128, v129
	v_add_f32_e32 v128, v128, v129
	v_fmamk_f32 v128, v128, 0x3c800000, v177
	v_rsq_f32_e32 v128, v128
	s_nop 0
	v_mul_f32_e32 v158, s70, v128
	v_add_u32_e32 v128, 0x200, v159
	v_and_b32_e32 v188, 0x1ffe0, v128
	v_lshl_add_u64 v[136:137], v[188:189], 0, v[142:143]
	v_lshl_add_u64 v[160:161], v[136:137], 3, s[40:41]
	s_nop 0
	v_pk_mul_f32 v[164:165], v[116:117], v[158:159] op_sel_hi:[1,0]
	v_pk_mul_f32 v[166:167], v[118:119], v[158:159] op_sel_hi:[1,0]
	v_or_b32_e32 v188, 16, v188
	s_waitcnt vmcnt(6)
	v_pk_mul_f32 v[132:133], v[198:199], v[164:165]
	v_pk_mul_f32 v[134:135], v[200:201], v[166:167]
	v_pk_mul_f32 v[166:167], v[248:249], v[132:133]
	v_pk_mul_f32 v[132:133], v[248:249], v[132:133] op_sel:[1,0] op_sel_hi:[0,1]
	v_add_f32_e32 v169, v132, v133
	v_pk_mul_f32 v[132:133], v[250:251], v[134:135] op_sel:[1,0] op_sel_hi:[0,1]
	v_add_f32_e32 v171, v132, v133
	v_pk_mul_f32 v[132:133], v[108:109], v[158:159] op_sel_hi:[1,0]
	v_pk_mul_f32 v[164:165], v[250:251], v[134:135]
	v_pk_mul_f32 v[134:135], v[110:111], v[158:159] op_sel_hi:[1,0]
	v_pk_mul_f32 v[128:129], v[194:195], v[132:133]
	v_pk_mul_f32 v[130:131], v[196:197], v[134:135]
	v_pk_mul_f32 v[134:135], v[244:245], v[128:129]
	v_pk_mul_f32 v[128:129], v[244:245], v[128:129] op_sel:[1,0] op_sel_hi:[0,1]
	v_add_f32_e32 v173, v128, v129
	v_pk_mul_f32 v[128:129], v[246:247], v[130:131] op_sel:[1,0] op_sel_hi:[0,1]
	v_pk_mul_f32 v[132:133], v[246:247], v[130:131]
	v_add_f32_e32 v176, v128, v129
	v_lshl_add_u64 v[128:129], v[188:189], 0, v[142:143]
	v_sub_f32_e32 v172, v134, v135
	v_sub_f32_e32 v174, v132, v133
	v_lshl_add_u64 v[136:137], v[128:129], 3, s[40:41]
	s_nop 0
	v_sub_f32_e32 v170, v164, v165
	v_pk_mul_f32 v[164:165], v[96:97], v[158:159] op_sel_hi:[1,0]
	v_sub_f32_e32 v168, v166, v167
	v_pk_mul_f32 v[166:167], v[98:99], v[158:159] op_sel_hi:[1,0]
	v_pk_mul_f32 v[160:161], v[206:207], v[164:165]
	v_pk_mul_f32 v[162:163], v[208:209], v[166:167]
	v_pk_mul_f32 v[166:167], v[210:211], v[160:161]
	v_pk_mul_f32 v[136:137], v[210:211], v[160:161] op_sel:[1,0] op_sel_hi:[0,1]
	v_add_f32_e32 v160, v136, v137
	v_pk_mul_f32 v[136:137], v[212:213], v[162:163] op_sel:[1,0] op_sel_hi:[0,1]
	v_pk_mul_f32 v[164:165], v[212:213], v[162:163]
	v_add_f32_e32 v162, v136, v137
	v_pk_mul_f32 v[136:137], v[88:89], v[158:159] op_sel_hi:[1,0]
	v_pk_mul_f32 v[138:139], v[90:91], v[158:159] op_sel_hi:[1,0]
	v_pk_mul_f32 v[132:133], v[202:203], v[136:137]
	v_pk_mul_f32 v[134:135], v[204:205], v[138:139]
	v_pk_mul_f32 v[138:139], v[178:179], v[132:133]
	v_pk_mul_f32 v[128:129], v[178:179], v[132:133] op_sel:[1,0] op_sel_hi:[0,1]
	v_sub_f32_e32 v138, v138, v139
	v_add_f32_e32 v139, v128, v129
	v_pk_mul_f32 v[128:129], v[180:181], v[134:135] op_sel:[1,0] op_sel_hi:[0,1]
	v_add_co_u32_e32 v132, vcc, s16, v156
	v_pk_mul_f32 v[136:137], v[180:181], v[134:135]
	v_add_f32_e32 v134, v128, v129
	v_cvt_pk_bf16_f32 v128, v168, v169
	v_cvt_pk_bf16_f32 v129, v170, v171
	v_addc_co_u32_e32 v133, vcc, 0, v157, vcc
	v_sub_f32_e32 v166, v166, v167
	v_sub_f32_e32 v161, v164, v165
	v_cvt_pk_bf16_f32 v130, v172, v173
	v_cvt_pk_bf16_f32 v131, v174, v176
	global_store_dwordx4 v[132:133], v[128:131], off
	v_sub_f32_e32 v136, v136, v137
	s_mov_b32 s16, 0x20000
	v_cvt_pk_bf16_f32 v128, v166, v160
	v_cvt_pk_bf16_f32 v129, v161, v162
	v_cvt_pk_bf16_f32 v130, v138, v139
	v_cvt_pk_bf16_f32 v131, v136, v134
	global_store_dwordx4 v[132:133], v[128:131], off offset:64
	s_nop 1
	v_add_u32_e32 v222, 0x600, v226
	v_and_b32_e32 v222, 0x1ffe0, v222
	v_lshl_add_u64 v[182:183], v[222:223], 0, v[224:225]
	v_lshl_add_u64 v[182:183], v[182:183], 3, s[40:41]
	global_load_dwordx4 v[244:247], v[182:183], off offset:16
	global_load_dwordx4 v[248:251], v[182:183], off
	v_or_b32_e32 v222, 16, v222
	v_lshl_add_u64 v[182:183], v[222:223], 0, v[224:225]
	v_lshl_add_u64 v[182:183], v[182:183], 3, s[40:41]
	global_load_dwordx4 v[178:181], v[182:183], off offset:16
	global_load_dwordx4 v[210:213], v[182:183], off
	v_mul_f32_e32 v128, v101, v101
	v_mul_f32_e32 v129, v103, v103
	v_fmac_f32_e32 v128, v100, v100
	v_fmac_f32_e32 v129, v102, v102
	v_add_f32_e32 v128, v128, v129
	v_mul_f32_e32 v129, v93, v93
	v_mul_f32_e32 v130, v95, v95
	v_fmac_f32_e32 v129, v92, v92
	v_fmac_f32_e32 v130, v94, v94
	v_add_f32_e32 v129, v129, v130
	v_add_f32_e32 v128, v128, v129
	v_mul_f32_e32 v129, v81, v81
	v_mul_f32_e32 v130, v83, v83
	v_fmac_f32_e32 v129, v80, v80
	v_fmac_f32_e32 v130, v82, v82
	v_add_f32_e32 v129, v129, v130
	v_add_f32_e32 v128, v128, v129
	v_mul_f32_e32 v129, v73, v73
	v_mul_f32_e32 v130, v75, v75
	v_fmac_f32_e32 v129, v72, v72
	v_fmac_f32_e32 v130, v74, v74
	v_add_f32_e32 v129, v129, v130
	v_add_f32_e32 v128, v128, v129
	v_mov_b32_e32 v129, v128
	s_nop 1
	v_permlane16_swap_b32_e32 v128, v129
	v_add_f32_e32 v128, v128, v129
	v_mov_b32_e32 v129, v128
	s_nop 1
	v_permlane32_swap_b32_e32 v128, v129
	v_add_f32_e32 v128, v128, v129
	v_fmamk_f32 v128, v128, 0x3c800000, v177
	v_rsq_f32_e32 v128, v128
	s_nop 0
	v_mul_f32_e32 v158, s70, v128
	v_add_u32_e32 v128, 0x400, v159
	v_and_b32_e32 v188, 0x1ffe0, v128
	v_lshl_add_u64 v[136:137], v[188:189], 0, v[142:143]
	v_lshl_add_u64 v[160:161], v[136:137], 3, s[40:41]
	s_nop 0
	v_pk_mul_f32 v[164:165], v[100:101], v[158:159] op_sel_hi:[1,0]
	v_pk_mul_f32 v[166:167], v[102:103], v[158:159] op_sel_hi:[1,0]
	v_or_b32_e32 v188, 16, v188
	s_waitcnt vmcnt(6)
	v_pk_mul_f32 v[132:133], v[198:199], v[164:165]
	v_pk_mul_f32 v[134:135], v[200:201], v[166:167]
	v_pk_mul_f32 v[166:167], v[232:233], v[132:133]
	v_pk_mul_f32 v[132:133], v[232:233], v[132:133] op_sel:[1,0] op_sel_hi:[0,1]
	v_add_f32_e32 v169, v132, v133
	v_pk_mul_f32 v[132:133], v[234:235], v[134:135] op_sel:[1,0] op_sel_hi:[0,1]
	v_add_f32_e32 v171, v132, v133
	v_pk_mul_f32 v[132:133], v[92:93], v[158:159] op_sel_hi:[1,0]
	v_pk_mul_f32 v[164:165], v[234:235], v[134:135]
	v_pk_mul_f32 v[134:135], v[94:95], v[158:159] op_sel_hi:[1,0]
	v_pk_mul_f32 v[128:129], v[194:195], v[132:133]
	v_pk_mul_f32 v[130:131], v[196:197], v[134:135]
	v_pk_mul_f32 v[134:135], v[228:229], v[128:129]
	v_pk_mul_f32 v[128:129], v[228:229], v[128:129] op_sel:[1,0] op_sel_hi:[0,1]
	v_add_f32_e32 v173, v128, v129
	v_pk_mul_f32 v[128:129], v[230:231], v[130:131] op_sel:[1,0] op_sel_hi:[0,1]
	v_pk_mul_f32 v[132:133], v[230:231], v[130:131]
	v_add_f32_e32 v176, v128, v129
	v_lshl_add_u64 v[128:129], v[188:189], 0, v[142:143]
	v_sub_f32_e32 v172, v134, v135
	v_sub_f32_e32 v174, v132, v133
	v_lshl_add_u64 v[136:137], v[128:129], 3, s[40:41]
	s_nop 0
	v_sub_f32_e32 v170, v164, v165
	v_pk_mul_f32 v[164:165], v[80:81], v[158:159] op_sel_hi:[1,0]
	v_sub_f32_e32 v168, v166, v167
	v_pk_mul_f32 v[166:167], v[82:83], v[158:159] op_sel_hi:[1,0]
	v_pk_mul_f32 v[160:161], v[206:207], v[164:165]
	v_pk_mul_f32 v[162:163], v[208:209], v[166:167]
	v_pk_mul_f32 v[166:167], v[240:241], v[160:161]
	v_pk_mul_f32 v[136:137], v[240:241], v[160:161] op_sel:[1,0] op_sel_hi:[0,1]
	v_add_f32_e32 v160, v136, v137
	v_pk_mul_f32 v[136:137], v[242:243], v[162:163] op_sel:[1,0] op_sel_hi:[0,1]
	v_pk_mul_f32 v[164:165], v[242:243], v[162:163]
	v_add_f32_e32 v162, v136, v137
	v_pk_mul_f32 v[136:137], v[72:73], v[158:159] op_sel_hi:[1,0]
	v_pk_mul_f32 v[138:139], v[74:75], v[158:159] op_sel_hi:[1,0]
	v_pk_mul_f32 v[132:133], v[202:203], v[136:137]
	v_pk_mul_f32 v[134:135], v[204:205], v[138:139]
	v_pk_mul_f32 v[138:139], v[236:237], v[132:133]
	v_pk_mul_f32 v[128:129], v[236:237], v[132:133] op_sel:[1,0] op_sel_hi:[0,1]
	v_sub_f32_e32 v138, v138, v139
	v_add_f32_e32 v139, v128, v129
	v_pk_mul_f32 v[128:129], v[238:239], v[134:135] op_sel:[1,0] op_sel_hi:[0,1]
	v_add_co_u32_e32 v132, vcc, s16, v156
	v_pk_mul_f32 v[136:137], v[238:239], v[134:135]
	v_add_f32_e32 v134, v128, v129
	v_cvt_pk_bf16_f32 v128, v168, v169
	v_cvt_pk_bf16_f32 v129, v170, v171
	v_addc_co_u32_e32 v133, vcc, 0, v157, vcc
	v_sub_f32_e32 v166, v166, v167
	v_sub_f32_e32 v161, v164, v165
	v_cvt_pk_bf16_f32 v130, v172, v173
	v_cvt_pk_bf16_f32 v131, v174, v176
	global_store_dwordx4 v[132:133], v[128:131], off
	v_sub_f32_e32 v136, v136, v137
	s_mov_b32 s16, 0x30000
	v_cvt_pk_bf16_f32 v128, v166, v160
	v_cvt_pk_bf16_f32 v129, v161, v162
	v_cvt_pk_bf16_f32 v130, v138, v139
	v_cvt_pk_bf16_f32 v131, v136, v134
	global_store_dwordx4 v[132:133], v[128:131], off offset:64
	s_nop 1
	v_add_u32_e32 v222, 0x1000, v226
	v_and_b32_e32 v222, 0x1ffe0, v222
	v_lshl_add_u64 v[182:183], v[222:223], 0, v[224:225]
	v_lshl_add_u64 v[182:183], v[182:183], 3, s[40:41]
	global_load_dwordx4 v[228:231], v[182:183], off offset:16
	global_load_dwordx4 v[232:235], v[182:183], off
	v_or_b32_e32 v222, 16, v222
	v_lshl_add_u64 v[182:183], v[222:223], 0, v[224:225]
	v_lshl_add_u64 v[182:183], v[182:183], 3, s[40:41]
	global_load_dwordx4 v[236:239], v[182:183], off offset:16
	global_load_dwordx4 v[240:243], v[182:183], off
	v_mul_f32_e32 v128, v85, v85
	v_mul_f32_e32 v129, v87, v87
	v_fmac_f32_e32 v128, v84, v84
	v_fmac_f32_e32 v129, v86, v86
	v_add_f32_e32 v128, v128, v129
	v_mul_f32_e32 v129, v77, v77
	v_mul_f32_e32 v130, v79, v79
	v_fmac_f32_e32 v129, v76, v76
	v_fmac_f32_e32 v130, v78, v78
	v_add_f32_e32 v129, v129, v130
	v_add_f32_e32 v128, v128, v129
	v_mul_f32_e32 v129, v69, v69
	v_mul_f32_e32 v130, v71, v71
	v_fmac_f32_e32 v129, v68, v68
	v_fmac_f32_e32 v130, v70, v70
	v_add_f32_e32 v129, v129, v130
	v_add_f32_e32 v128, v128, v129
	v_mul_f32_e32 v129, v65, v65
	v_mul_f32_e32 v130, v67, v67
	v_fmac_f32_e32 v129, v64, v64
	v_fmac_f32_e32 v130, v66, v66
	v_add_f32_e32 v129, v129, v130
	v_add_f32_e32 v128, v128, v129
	v_mov_b32_e32 v129, v128
	s_nop 1
	v_permlane16_swap_b32_e32 v128, v129
	v_add_f32_e32 v128, v128, v129
	v_mov_b32_e32 v129, v128
	s_nop 1
	v_permlane32_swap_b32_e32 v128, v129
	v_add_f32_e32 v128, v128, v129
	v_fmamk_f32 v128, v128, 0x3c800000, v177
	v_rsq_f32_e32 v128, v128
	s_nop 0
	v_mul_f32_e32 v158, s70, v128
	v_add_u32_e32 v128, 0x600, v159
	v_and_b32_e32 v188, 0x1ffe0, v128
	v_lshl_add_u64 v[136:137], v[188:189], 0, v[142:143]
	v_lshl_add_u64 v[160:161], v[136:137], 3, s[40:41]
	s_nop 0
	v_pk_mul_f32 v[164:165], v[84:85], v[158:159] op_sel_hi:[1,0]
	v_pk_mul_f32 v[166:167], v[86:87], v[158:159] op_sel_hi:[1,0]
	v_or_b32_e32 v188, 16, v188
	s_waitcnt vmcnt(6)
	v_pk_mul_f32 v[132:133], v[198:199], v[164:165]
	v_pk_mul_f32 v[134:135], v[200:201], v[166:167]
	v_pk_mul_f32 v[166:167], v[248:249], v[132:133]
	v_pk_mul_f32 v[132:133], v[248:249], v[132:133] op_sel:[1,0] op_sel_hi:[0,1]
	v_add_f32_e32 v169, v132, v133
	v_pk_mul_f32 v[132:133], v[250:251], v[134:135] op_sel:[1,0] op_sel_hi:[0,1]
	v_add_f32_e32 v171, v132, v133
	v_pk_mul_f32 v[132:133], v[76:77], v[158:159] op_sel_hi:[1,0]
	v_pk_mul_f32 v[164:165], v[250:251], v[134:135]
	v_pk_mul_f32 v[134:135], v[78:79], v[158:159] op_sel_hi:[1,0]
	v_pk_mul_f32 v[128:129], v[194:195], v[132:133]
	v_pk_mul_f32 v[130:131], v[196:197], v[134:135]
	v_pk_mul_f32 v[134:135], v[244:245], v[128:129]
	v_pk_mul_f32 v[128:129], v[244:245], v[128:129] op_sel:[1,0] op_sel_hi:[0,1]
	v_add_f32_e32 v173, v128, v129
	v_pk_mul_f32 v[128:129], v[246:247], v[130:131] op_sel:[1,0] op_sel_hi:[0,1]
	v_pk_mul_f32 v[132:133], v[246:247], v[130:131]
	v_add_f32_e32 v176, v128, v129
	v_lshl_add_u64 v[128:129], v[188:189], 0, v[142:143]
	v_sub_f32_e32 v172, v134, v135
	v_sub_f32_e32 v174, v132, v133
	v_lshl_add_u64 v[136:137], v[128:129], 3, s[40:41]
	s_nop 0
	v_sub_f32_e32 v170, v164, v165
	v_pk_mul_f32 v[164:165], v[68:69], v[158:159] op_sel_hi:[1,0]
	v_sub_f32_e32 v168, v166, v167
	v_pk_mul_f32 v[166:167], v[70:71], v[158:159] op_sel_hi:[1,0]
	v_pk_mul_f32 v[160:161], v[206:207], v[164:165]
	v_pk_mul_f32 v[162:163], v[208:209], v[166:167]
	v_pk_mul_f32 v[166:167], v[210:211], v[160:161]
	v_pk_mul_f32 v[136:137], v[210:211], v[160:161] op_sel:[1,0] op_sel_hi:[0,1]
	v_add_f32_e32 v160, v136, v137
	v_pk_mul_f32 v[136:137], v[212:213], v[162:163] op_sel:[1,0] op_sel_hi:[0,1]
	v_pk_mul_f32 v[164:165], v[212:213], v[162:163]
	v_add_f32_e32 v162, v136, v137
	v_pk_mul_f32 v[136:137], v[64:65], v[158:159] op_sel_hi:[1,0]
	v_pk_mul_f32 v[138:139], v[66:67], v[158:159] op_sel_hi:[1,0]
	v_pk_mul_f32 v[132:133], v[202:203], v[136:137]
	v_pk_mul_f32 v[134:135], v[204:205], v[138:139]
	v_pk_mul_f32 v[138:139], v[178:179], v[132:133]
	v_pk_mul_f32 v[128:129], v[178:179], v[132:133] op_sel:[1,0] op_sel_hi:[0,1]
	v_sub_f32_e32 v138, v138, v139
	v_add_f32_e32 v139, v128, v129
	v_pk_mul_f32 v[128:129], v[180:181], v[134:135] op_sel:[1,0] op_sel_hi:[0,1]
	v_add_co_u32_e32 v132, vcc, s16, v156
	v_pk_mul_f32 v[136:137], v[180:181], v[134:135]
	v_add_f32_e32 v134, v128, v129
	v_cvt_pk_bf16_f32 v128, v168, v169
	v_cvt_pk_bf16_f32 v129, v170, v171
	v_addc_co_u32_e32 v133, vcc, 0, v157, vcc
	v_sub_f32_e32 v166, v166, v167
	v_sub_f32_e32 v161, v164, v165
	v_cvt_pk_bf16_f32 v130, v172, v173
	v_cvt_pk_bf16_f32 v131, v174, v176
	global_store_dwordx4 v[132:133], v[128:131], off
	v_sub_f32_e32 v136, v136, v137
	s_mov_b32 s16, 0x80000
	v_cvt_pk_bf16_f32 v128, v166, v160
	v_cvt_pk_bf16_f32 v129, v161, v162
	v_cvt_pk_bf16_f32 v130, v138, v139
	v_cvt_pk_bf16_f32 v131, v136, v134
	global_store_dwordx4 v[132:133], v[128:131], off offset:64
	s_nop 1
	v_add_u32_e32 v222, 0x1200, v226
	v_and_b32_e32 v222, 0x1ffe0, v222
	v_lshl_add_u64 v[182:183], v[222:223], 0, v[224:225]
	v_lshl_add_u64 v[182:183], v[182:183], 3, s[40:41]
	global_load_dwordx4 v[244:247], v[182:183], off offset:16
	global_load_dwordx4 v[248:251], v[182:183], off
	v_or_b32_e32 v222, 16, v222
	v_lshl_add_u64 v[182:183], v[222:223], 0, v[224:225]
	v_lshl_add_u64 v[182:183], v[182:183], 3, s[40:41]
	global_load_dwordx4 v[178:181], v[182:183], off offset:16
	global_load_dwordx4 v[210:213], v[182:183], off
	v_mul_f32_e32 v128, v61, v61
	v_mul_f32_e32 v129, v63, v63
	v_fmac_f32_e32 v128, v60, v60
	v_fmac_f32_e32 v129, v62, v62
	v_add_f32_e32 v128, v128, v129
	v_mul_f32_e32 v129, v57, v57
	v_mul_f32_e32 v130, v59, v59
	v_fmac_f32_e32 v129, v56, v56
	v_fmac_f32_e32 v130, v58, v58
	v_add_f32_e32 v129, v129, v130
	v_add_f32_e32 v128, v128, v129
	v_mul_f32_e32 v129, v49, v49
	v_mul_f32_e32 v130, v51, v51
	v_fmac_f32_e32 v129, v48, v48
	v_fmac_f32_e32 v130, v50, v50
	v_add_f32_e32 v129, v129, v130
	v_add_f32_e32 v128, v128, v129
	v_mul_f32_e32 v129, v41, v41
	v_mul_f32_e32 v130, v43, v43
	v_fmac_f32_e32 v129, v40, v40
	v_fmac_f32_e32 v130, v42, v42
	v_add_f32_e32 v129, v129, v130
	v_add_f32_e32 v128, v128, v129
	v_mov_b32_e32 v129, v128
	s_nop 1
	v_permlane16_swap_b32_e32 v128, v129
	v_add_f32_e32 v128, v128, v129
	v_mov_b32_e32 v129, v128
	s_nop 1
	v_permlane32_swap_b32_e32 v128, v129
	v_add_f32_e32 v128, v128, v129
	v_fmamk_f32 v128, v128, 0x3c800000, v177
	v_rsq_f32_e32 v128, v128
	s_nop 0
	v_mul_f32_e32 v158, s70, v128
	v_add_u32_e32 v128, 0x1000, v159
	v_and_b32_e32 v188, 0x1ffe0, v128
	v_lshl_add_u64 v[136:137], v[188:189], 0, v[142:143]
	v_lshl_add_u64 v[160:161], v[136:137], 3, s[40:41]
	s_nop 0
	v_pk_mul_f32 v[164:165], v[60:61], v[158:159] op_sel_hi:[1,0]
	v_pk_mul_f32 v[166:167], v[62:63], v[158:159] op_sel_hi:[1,0]
	v_or_b32_e32 v188, 16, v188
	s_waitcnt vmcnt(6)
	v_pk_mul_f32 v[132:133], v[198:199], v[164:165]
	v_pk_mul_f32 v[134:135], v[200:201], v[166:167]
	v_pk_mul_f32 v[166:167], v[232:233], v[132:133]
	v_pk_mul_f32 v[132:133], v[232:233], v[132:133] op_sel:[1,0] op_sel_hi:[0,1]
	v_add_f32_e32 v169, v132, v133
	v_pk_mul_f32 v[132:133], v[234:235], v[134:135] op_sel:[1,0] op_sel_hi:[0,1]
	v_add_f32_e32 v171, v132, v133
	v_pk_mul_f32 v[132:133], v[56:57], v[158:159] op_sel_hi:[1,0]
	v_pk_mul_f32 v[164:165], v[234:235], v[134:135]
	v_pk_mul_f32 v[134:135], v[58:59], v[158:159] op_sel_hi:[1,0]
	v_pk_mul_f32 v[128:129], v[194:195], v[132:133]
	v_pk_mul_f32 v[130:131], v[196:197], v[134:135]
	v_pk_mul_f32 v[134:135], v[228:229], v[128:129]
	v_pk_mul_f32 v[128:129], v[228:229], v[128:129] op_sel:[1,0] op_sel_hi:[0,1]
	v_add_f32_e32 v173, v128, v129
	v_pk_mul_f32 v[128:129], v[230:231], v[130:131] op_sel:[1,0] op_sel_hi:[0,1]
	v_pk_mul_f32 v[132:133], v[230:231], v[130:131]
	v_add_f32_e32 v176, v128, v129
	v_lshl_add_u64 v[128:129], v[188:189], 0, v[142:143]
	v_sub_f32_e32 v172, v134, v135
	v_sub_f32_e32 v174, v132, v133
	v_lshl_add_u64 v[136:137], v[128:129], 3, s[40:41]
	s_nop 0
	v_sub_f32_e32 v170, v164, v165
	v_pk_mul_f32 v[164:165], v[48:49], v[158:159] op_sel_hi:[1,0]
	v_sub_f32_e32 v168, v166, v167
	v_pk_mul_f32 v[166:167], v[50:51], v[158:159] op_sel_hi:[1,0]
	v_pk_mul_f32 v[160:161], v[206:207], v[164:165]
	v_pk_mul_f32 v[162:163], v[208:209], v[166:167]
	v_pk_mul_f32 v[166:167], v[240:241], v[160:161]
	v_pk_mul_f32 v[136:137], v[240:241], v[160:161] op_sel:[1,0] op_sel_hi:[0,1]
	v_add_f32_e32 v160, v136, v137
	v_pk_mul_f32 v[136:137], v[242:243], v[162:163] op_sel:[1,0] op_sel_hi:[0,1]
	v_pk_mul_f32 v[164:165], v[242:243], v[162:163]
	v_add_f32_e32 v162, v136, v137
	v_pk_mul_f32 v[136:137], v[40:41], v[158:159] op_sel_hi:[1,0]
	v_pk_mul_f32 v[138:139], v[42:43], v[158:159] op_sel_hi:[1,0]
	v_pk_mul_f32 v[132:133], v[202:203], v[136:137]
	v_pk_mul_f32 v[134:135], v[204:205], v[138:139]
	v_pk_mul_f32 v[138:139], v[236:237], v[132:133]
	v_pk_mul_f32 v[128:129], v[236:237], v[132:133] op_sel:[1,0] op_sel_hi:[0,1]
	v_sub_f32_e32 v138, v138, v139
	v_add_f32_e32 v139, v128, v129
	v_pk_mul_f32 v[128:129], v[238:239], v[134:135] op_sel:[1,0] op_sel_hi:[0,1]
	v_add_co_u32_e32 v132, vcc, s16, v156
	v_pk_mul_f32 v[136:137], v[238:239], v[134:135]
	v_add_f32_e32 v134, v128, v129
	v_cvt_pk_bf16_f32 v128, v168, v169
	v_cvt_pk_bf16_f32 v129, v170, v171
	v_addc_co_u32_e32 v133, vcc, 0, v157, vcc
	v_sub_f32_e32 v166, v166, v167
	v_sub_f32_e32 v161, v164, v165
	v_cvt_pk_bf16_f32 v130, v172, v173
	v_cvt_pk_bf16_f32 v131, v174, v176
	global_store_dwordx4 v[132:133], v[128:131], off
	v_sub_f32_e32 v136, v136, v137
	s_mov_b32 s16, 0x90000
	v_cvt_pk_bf16_f32 v128, v166, v160
	v_cvt_pk_bf16_f32 v129, v161, v162
	v_cvt_pk_bf16_f32 v130, v138, v139
	v_cvt_pk_bf16_f32 v131, v136, v134
	global_store_dwordx4 v[132:133], v[128:131], off offset:64
	s_nop 1
	v_add_u32_e32 v222, 0x1400, v226
	v_and_b32_e32 v222, 0x1ffe0, v222
	v_lshl_add_u64 v[182:183], v[222:223], 0, v[224:225]
	v_lshl_add_u64 v[182:183], v[182:183], 3, s[40:41]
	global_load_dwordx4 v[228:231], v[182:183], off offset:16
	global_load_dwordx4 v[232:235], v[182:183], off
	v_or_b32_e32 v222, 16, v222
	v_lshl_add_u64 v[182:183], v[222:223], 0, v[224:225]
	v_lshl_add_u64 v[182:183], v[182:183], 3, s[40:41]
	global_load_dwordx4 v[236:239], v[182:183], off offset:16
	global_load_dwordx4 v[240:243], v[182:183], off
	v_mul_f32_e32 v128, v53, v53
	v_mul_f32_e32 v129, v55, v55
	v_fmac_f32_e32 v128, v52, v52
	v_fmac_f32_e32 v129, v54, v54
	v_add_f32_e32 v128, v128, v129
	v_mul_f32_e32 v129, v45, v45
	v_mul_f32_e32 v130, v47, v47
	v_fmac_f32_e32 v129, v44, v44
	v_fmac_f32_e32 v130, v46, v46
	v_add_f32_e32 v129, v129, v130
	v_add_f32_e32 v128, v128, v129
	v_mul_f32_e32 v129, v33, v33
	v_mul_f32_e32 v130, v35, v35
	v_fmac_f32_e32 v129, v32, v32
	v_fmac_f32_e32 v130, v34, v34
	v_add_f32_e32 v129, v129, v130
	v_add_f32_e32 v128, v128, v129
	v_mul_f32_e32 v129, v25, v25
	v_mul_f32_e32 v130, v27, v27
	v_fmac_f32_e32 v129, v24, v24
	v_fmac_f32_e32 v130, v26, v26
	v_add_f32_e32 v129, v129, v130
	v_add_f32_e32 v128, v128, v129
	v_mov_b32_e32 v129, v128
	s_nop 1
	v_permlane16_swap_b32_e32 v128, v129
	v_add_f32_e32 v128, v128, v129
	v_mov_b32_e32 v129, v128
	s_nop 1
	v_permlane32_swap_b32_e32 v128, v129
	v_add_f32_e32 v128, v128, v129
	v_fmamk_f32 v128, v128, 0x3c800000, v177
	v_rsq_f32_e32 v128, v128
	s_nop 0
	v_mul_f32_e32 v158, s70, v128
	v_add_u32_e32 v128, 0x1200, v159
	v_and_b32_e32 v188, 0x1ffe0, v128
	v_lshl_add_u64 v[136:137], v[188:189], 0, v[142:143]
	v_lshl_add_u64 v[160:161], v[136:137], 3, s[40:41]
	s_nop 0
	v_pk_mul_f32 v[164:165], v[52:53], v[158:159] op_sel_hi:[1,0]
	v_pk_mul_f32 v[166:167], v[54:55], v[158:159] op_sel_hi:[1,0]
	v_or_b32_e32 v188, 16, v188
	s_waitcnt vmcnt(6)
	v_pk_mul_f32 v[132:133], v[198:199], v[164:165]
	v_pk_mul_f32 v[134:135], v[200:201], v[166:167]
	v_pk_mul_f32 v[166:167], v[248:249], v[132:133]
	v_pk_mul_f32 v[132:133], v[248:249], v[132:133] op_sel:[1,0] op_sel_hi:[0,1]
	v_add_f32_e32 v169, v132, v133
	v_pk_mul_f32 v[132:133], v[250:251], v[134:135] op_sel:[1,0] op_sel_hi:[0,1]
	v_add_f32_e32 v171, v132, v133
	v_pk_mul_f32 v[132:133], v[44:45], v[158:159] op_sel_hi:[1,0]
	v_pk_mul_f32 v[164:165], v[250:251], v[134:135]
	v_pk_mul_f32 v[134:135], v[46:47], v[158:159] op_sel_hi:[1,0]
	v_pk_mul_f32 v[128:129], v[194:195], v[132:133]
	v_pk_mul_f32 v[130:131], v[196:197], v[134:135]
	v_pk_mul_f32 v[134:135], v[244:245], v[128:129]
	v_pk_mul_f32 v[128:129], v[244:245], v[128:129] op_sel:[1,0] op_sel_hi:[0,1]
	v_add_f32_e32 v173, v128, v129
	v_pk_mul_f32 v[128:129], v[246:247], v[130:131] op_sel:[1,0] op_sel_hi:[0,1]
	v_pk_mul_f32 v[132:133], v[246:247], v[130:131]
	v_add_f32_e32 v176, v128, v129
	v_lshl_add_u64 v[128:129], v[188:189], 0, v[142:143]
	v_sub_f32_e32 v172, v134, v135
	v_sub_f32_e32 v174, v132, v133
	v_lshl_add_u64 v[136:137], v[128:129], 3, s[40:41]
	s_nop 0
	v_sub_f32_e32 v170, v164, v165
	v_pk_mul_f32 v[164:165], v[32:33], v[158:159] op_sel_hi:[1,0]
	v_sub_f32_e32 v168, v166, v167
	v_pk_mul_f32 v[166:167], v[34:35], v[158:159] op_sel_hi:[1,0]
	v_pk_mul_f32 v[160:161], v[206:207], v[164:165]
	v_pk_mul_f32 v[162:163], v[208:209], v[166:167]
	v_pk_mul_f32 v[166:167], v[210:211], v[160:161]
	v_pk_mul_f32 v[136:137], v[210:211], v[160:161] op_sel:[1,0] op_sel_hi:[0,1]
	v_add_f32_e32 v160, v136, v137
	v_pk_mul_f32 v[136:137], v[212:213], v[162:163] op_sel:[1,0] op_sel_hi:[0,1]
	v_pk_mul_f32 v[164:165], v[212:213], v[162:163]
	v_add_f32_e32 v162, v136, v137
	v_pk_mul_f32 v[136:137], v[24:25], v[158:159] op_sel_hi:[1,0]
	v_pk_mul_f32 v[138:139], v[26:27], v[158:159] op_sel_hi:[1,0]
	v_pk_mul_f32 v[132:133], v[202:203], v[136:137]
	v_pk_mul_f32 v[134:135], v[204:205], v[138:139]
	v_pk_mul_f32 v[138:139], v[178:179], v[132:133]
	v_pk_mul_f32 v[128:129], v[178:179], v[132:133] op_sel:[1,0] op_sel_hi:[0,1]
	v_sub_f32_e32 v138, v138, v139
	v_add_f32_e32 v139, v128, v129
	v_pk_mul_f32 v[128:129], v[180:181], v[134:135] op_sel:[1,0] op_sel_hi:[0,1]
	v_add_co_u32_e32 v132, vcc, s16, v156
	v_pk_mul_f32 v[136:137], v[180:181], v[134:135]
	v_add_f32_e32 v134, v128, v129
	v_cvt_pk_bf16_f32 v128, v168, v169
	v_cvt_pk_bf16_f32 v129, v170, v171
	v_addc_co_u32_e32 v133, vcc, 0, v157, vcc
	v_sub_f32_e32 v166, v166, v167
	v_sub_f32_e32 v161, v164, v165
	v_cvt_pk_bf16_f32 v130, v172, v173
	v_cvt_pk_bf16_f32 v131, v174, v176
	global_store_dwordx4 v[132:133], v[128:131], off
	v_sub_f32_e32 v136, v136, v137
	s_mov_b32 s16, 0xa0000
	v_cvt_pk_bf16_f32 v128, v166, v160
	v_cvt_pk_bf16_f32 v129, v161, v162
	v_cvt_pk_bf16_f32 v130, v138, v139
	v_cvt_pk_bf16_f32 v131, v136, v134
	global_store_dwordx4 v[132:133], v[128:131], off offset:64
	s_nop 1
	v_add_u32_e32 v222, 0x1600, v226
	v_and_b32_e32 v222, 0x1ffe0, v222
	v_lshl_add_u64 v[182:183], v[222:223], 0, v[224:225]
	v_lshl_add_u64 v[182:183], v[182:183], 3, s[40:41]
	global_load_dwordx4 v[244:247], v[182:183], off offset:16
	global_load_dwordx4 v[248:251], v[182:183], off
	v_or_b32_e32 v222, 16, v222
	v_lshl_add_u64 v[182:183], v[222:223], 0, v[224:225]
	v_lshl_add_u64 v[182:183], v[182:183], 3, s[40:41]
	global_load_dwordx4 v[178:181], v[182:183], off offset:16
	global_load_dwordx4 v[210:213], v[182:183], off
	v_mul_f32_e32 v128, v37, v37
	v_mul_f32_e32 v129, v39, v39
	v_fmac_f32_e32 v128, v36, v36
	v_fmac_f32_e32 v129, v38, v38
	v_add_f32_e32 v128, v128, v129
	v_mul_f32_e32 v129, v29, v29
	v_mul_f32_e32 v130, v31, v31
	v_fmac_f32_e32 v129, v28, v28
	v_fmac_f32_e32 v130, v30, v30
	v_add_f32_e32 v129, v129, v130
	v_add_f32_e32 v128, v128, v129
	v_mul_f32_e32 v129, v17, v17
	v_mul_f32_e32 v130, v19, v19
	v_fmac_f32_e32 v129, v16, v16
	v_fmac_f32_e32 v130, v18, v18
	v_add_f32_e32 v129, v129, v130
	v_add_f32_e32 v128, v128, v129
	v_mul_f32_e32 v129, v9, v9
	v_mul_f32_e32 v130, v11, v11
	v_fmac_f32_e32 v129, v8, v8
	v_fmac_f32_e32 v130, v10, v10
	v_add_f32_e32 v129, v129, v130
	v_add_f32_e32 v128, v128, v129
	v_mov_b32_e32 v129, v128
	s_nop 1
	v_permlane16_swap_b32_e32 v128, v129
	v_add_f32_e32 v128, v128, v129
	v_mov_b32_e32 v129, v128
	s_nop 1
	v_permlane32_swap_b32_e32 v128, v129
	v_add_f32_e32 v128, v128, v129
	v_fmamk_f32 v128, v128, 0x3c800000, v177
	v_rsq_f32_e32 v128, v128
	s_nop 0
	v_mul_f32_e32 v158, s70, v128
	v_add_u32_e32 v128, 0x1400, v159
	v_and_b32_e32 v188, 0x1ffe0, v128
	v_lshl_add_u64 v[136:137], v[188:189], 0, v[142:143]
	v_lshl_add_u64 v[160:161], v[136:137], 3, s[40:41]
	s_nop 0
	v_pk_mul_f32 v[164:165], v[36:37], v[158:159] op_sel_hi:[1,0]
	v_pk_mul_f32 v[166:167], v[38:39], v[158:159] op_sel_hi:[1,0]
	v_or_b32_e32 v188, 16, v188
	s_waitcnt vmcnt(6)
	v_pk_mul_f32 v[132:133], v[198:199], v[164:165]
	v_pk_mul_f32 v[134:135], v[200:201], v[166:167]
	v_pk_mul_f32 v[166:167], v[232:233], v[132:133]
	v_pk_mul_f32 v[132:133], v[232:233], v[132:133] op_sel:[1,0] op_sel_hi:[0,1]
	v_add_f32_e32 v169, v132, v133
	v_pk_mul_f32 v[132:133], v[234:235], v[134:135] op_sel:[1,0] op_sel_hi:[0,1]
	v_add_f32_e32 v171, v132, v133
	v_pk_mul_f32 v[132:133], v[28:29], v[158:159] op_sel_hi:[1,0]
	v_pk_mul_f32 v[164:165], v[234:235], v[134:135]
	v_pk_mul_f32 v[134:135], v[30:31], v[158:159] op_sel_hi:[1,0]
	v_pk_mul_f32 v[128:129], v[194:195], v[132:133]
	v_pk_mul_f32 v[130:131], v[196:197], v[134:135]
	v_pk_mul_f32 v[134:135], v[228:229], v[128:129]
	v_pk_mul_f32 v[128:129], v[228:229], v[128:129] op_sel:[1,0] op_sel_hi:[0,1]
	v_add_f32_e32 v173, v128, v129
	v_pk_mul_f32 v[128:129], v[230:231], v[130:131] op_sel:[1,0] op_sel_hi:[0,1]
	v_pk_mul_f32 v[132:133], v[230:231], v[130:131]
	v_add_f32_e32 v176, v128, v129
	v_lshl_add_u64 v[128:129], v[188:189], 0, v[142:143]
	v_sub_f32_e32 v172, v134, v135
	v_sub_f32_e32 v174, v132, v133
	v_lshl_add_u64 v[136:137], v[128:129], 3, s[40:41]
	s_nop 0
	v_sub_f32_e32 v170, v164, v165
	v_pk_mul_f32 v[164:165], v[16:17], v[158:159] op_sel_hi:[1,0]
	v_sub_f32_e32 v168, v166, v167
	v_pk_mul_f32 v[166:167], v[18:19], v[158:159] op_sel_hi:[1,0]
	v_pk_mul_f32 v[160:161], v[206:207], v[164:165]
	v_pk_mul_f32 v[162:163], v[208:209], v[166:167]
	v_pk_mul_f32 v[166:167], v[240:241], v[160:161]
	v_pk_mul_f32 v[136:137], v[240:241], v[160:161] op_sel:[1,0] op_sel_hi:[0,1]
	v_add_f32_e32 v160, v136, v137
	v_pk_mul_f32 v[136:137], v[242:243], v[162:163] op_sel:[1,0] op_sel_hi:[0,1]
	v_pk_mul_f32 v[164:165], v[242:243], v[162:163]
	v_add_f32_e32 v162, v136, v137
	v_pk_mul_f32 v[136:137], v[8:9], v[158:159] op_sel_hi:[1,0]
	v_pk_mul_f32 v[138:139], v[10:11], v[158:159] op_sel_hi:[1,0]
	v_pk_mul_f32 v[132:133], v[202:203], v[136:137]
	v_pk_mul_f32 v[134:135], v[204:205], v[138:139]
	v_pk_mul_f32 v[138:139], v[236:237], v[132:133]
	v_pk_mul_f32 v[128:129], v[236:237], v[132:133] op_sel:[1,0] op_sel_hi:[0,1]
	v_sub_f32_e32 v138, v138, v139
	v_add_f32_e32 v139, v128, v129
	v_pk_mul_f32 v[128:129], v[238:239], v[134:135] op_sel:[1,0] op_sel_hi:[0,1]
	v_add_co_u32_e32 v132, vcc, s16, v156
	v_pk_mul_f32 v[136:137], v[238:239], v[134:135]
	v_add_f32_e32 v134, v128, v129
	v_cvt_pk_bf16_f32 v128, v168, v169
	v_cvt_pk_bf16_f32 v129, v170, v171
	v_addc_co_u32_e32 v133, vcc, 0, v157, vcc
	v_sub_f32_e32 v166, v166, v167
	v_sub_f32_e32 v161, v164, v165
	v_cvt_pk_bf16_f32 v130, v172, v173
	v_cvt_pk_bf16_f32 v131, v174, v176
	global_store_dwordx4 v[132:133], v[128:131], off
	v_sub_f32_e32 v136, v136, v137
	s_nop 0
	v_cvt_pk_bf16_f32 v128, v166, v160
	v_cvt_pk_bf16_f32 v129, v161, v162
	v_cvt_pk_bf16_f32 v130, v138, v139
	v_cvt_pk_bf16_f32 v131, v136, v134
	global_store_dwordx4 v[132:133], v[128:131], off offset:64
	s_nop 1
	v_mul_f32_e32 v128, v21, v21
	v_mul_f32_e32 v129, v23, v23
	v_fmac_f32_e32 v128, v20, v20
	v_fmac_f32_e32 v129, v22, v22
	v_add_f32_e32 v128, v128, v129
	v_mul_f32_e32 v129, v13, v13
	v_mul_f32_e32 v130, v15, v15
	v_fmac_f32_e32 v129, v12, v12
	v_fmac_f32_e32 v130, v14, v14
	v_add_f32_e32 v129, v129, v130
	v_add_f32_e32 v128, v128, v129
	v_mul_f32_e32 v129, v5, v5
	v_mul_f32_e32 v130, v7, v7
	v_fmac_f32_e32 v129, v4, v4
	v_fmac_f32_e32 v130, v6, v6
	v_add_f32_e32 v129, v129, v130
	v_add_f32_e32 v128, v128, v129
	v_mul_f32_e32 v129, v1, v1
	v_mul_f32_e32 v130, v3, v3
	v_fmac_f32_e32 v129, v0, v0
	v_fmac_f32_e32 v130, v2, v2
	v_add_f32_e32 v129, v129, v130
	v_add_f32_e32 v128, v128, v129
	v_mov_b32_e32 v129, v128
	s_nop 1
	v_permlane16_swap_b32_e32 v128, v129
	v_add_f32_e32 v128, v128, v129
	v_mov_b32_e32 v129, v128
	s_nop 1
	v_permlane32_swap_b32_e32 v128, v129
	v_add_f32_e32 v128, v128, v129
	v_fmamk_f32 v128, v128, 0x3c800000, v177
	v_rsq_f32_e32 v128, v128
	s_nop 0
	v_mul_f32_e32 v158, s70, v128
	v_add_u32_e32 v128, 0x1600, v159
	v_and_b32_e32 v188, 0x1ffe0, v128
	v_lshl_add_u64 v[136:137], v[188:189], 0, v[142:143]
	v_lshl_add_u64 v[160:161], v[136:137], 3, s[40:41]
	s_nop 0
	v_pk_mul_f32 v[164:165], v[20:21], v[158:159] op_sel_hi:[1,0]
	v_pk_mul_f32 v[166:167], v[22:23], v[158:159] op_sel_hi:[1,0]
	v_or_b32_e32 v188, 16, v188
	s_waitcnt vmcnt(2)
	v_pk_mul_f32 v[132:133], v[198:199], v[164:165]
	v_pk_mul_f32 v[134:135], v[200:201], v[166:167]
	v_pk_mul_f32 v[166:167], v[248:249], v[132:133]
	v_pk_mul_f32 v[132:133], v[248:249], v[132:133] op_sel:[1,0] op_sel_hi:[0,1]
	v_pk_mul_f32 v[164:165], v[250:251], v[134:135]
	v_sub_f32_e32 v159, v166, v167
	v_add_f32_e32 v166, v132, v133
	v_pk_mul_f32 v[132:133], v[250:251], v[134:135] op_sel:[1,0] op_sel_hi:[0,1]
	v_sub_f32_e32 v164, v164, v165
	v_add_f32_e32 v165, v132, v133
	v_pk_mul_f32 v[132:133], v[12:13], v[158:159] op_sel_hi:[1,0]
	v_pk_mul_f32 v[134:135], v[14:15], v[158:159] op_sel_hi:[1,0]
	v_pk_mul_f32 v[128:129], v[194:195], v[132:133]
	v_pk_mul_f32 v[130:131], v[196:197], v[134:135]
	v_pk_mul_f32 v[134:135], v[244:245], v[128:129]
	v_pk_mul_f32 v[128:129], v[244:245], v[128:129] op_sel:[1,0] op_sel_hi:[0,1]
	v_add_f32_e32 v168, v128, v129
	v_pk_mul_f32 v[128:129], v[246:247], v[130:131] op_sel:[1,0] op_sel_hi:[0,1]
	v_pk_mul_f32 v[132:133], v[246:247], v[130:131]
	v_add_f32_e32 v170, v128, v129
	v_lshl_add_u64 v[128:129], v[188:189], 0, v[142:143]
	v_sub_f32_e32 v167, v134, v135
	v_sub_f32_e32 v169, v132, v133
	s_nop 0
	v_lshl_add_u64 v[136:137], v[128:129], 3, s[40:41]
	s_nop 0
	v_pk_mul_f32 v[160:161], v[4:5], v[158:159] op_sel_hi:[1,0]
	v_pk_mul_f32 v[162:163], v[6:7], v[158:159] op_sel_hi:[1,0]
	v_pk_mul_f32 v[140:141], v[206:207], v[160:161]
	v_pk_mul_f32 v[142:143], v[208:209], v[162:163]
	v_pk_mul_f32 v[162:163], v[210:211], v[140:141]
	v_pk_mul_f32 v[136:137], v[210:211], v[140:141] op_sel:[1,0] op_sel_hi:[0,1]
	v_add_f32_e32 v140, v136, v137
	v_pk_mul_f32 v[136:137], v[212:213], v[142:143] op_sel:[1,0] op_sel_hi:[0,1]
	v_pk_mul_f32 v[160:161], v[212:213], v[142:143]
	v_add_f32_e32 v142, v136, v137
	v_pk_mul_f32 v[136:137], v[0:1], v[158:159] op_sel_hi:[1,0]
	v_pk_mul_f32 v[138:139], v[2:3], v[158:159] op_sel_hi:[1,0]
	v_pk_mul_f32 v[132:133], v[202:203], v[136:137]
	v_pk_mul_f32 v[134:135], v[204:205], v[138:139]
	v_pk_mul_f32 v[138:139], v[178:179], v[132:133]
	v_pk_mul_f32 v[128:129], v[178:179], v[132:133] op_sel:[1,0] op_sel_hi:[0,1]
	v_sub_f32_e32 v138, v138, v139
	v_add_f32_e32 v139, v128, v129
	v_pk_mul_f32 v[128:129], v[180:181], v[134:135] op_sel:[1,0] op_sel_hi:[0,1]
	v_add_co_u32_e32 v132, vcc, 0xb0000, v156
	v_pk_mul_f32 v[136:137], v[180:181], v[134:135]
	v_add_f32_e32 v134, v128, v129
	v_cvt_pk_bf16_f32 v128, v159, v166
	v_cvt_pk_bf16_f32 v129, v164, v165
	v_cvt_pk_bf16_f32 v130, v167, v168
	v_cvt_pk_bf16_f32 v131, v169, v170
	v_addc_co_u32_e32 v133, vcc, 0, v157, vcc
	v_sub_f32_e32 v162, v162, v163
	v_sub_f32_e32 v141, v160, v161
	v_sub_f32_e32 v136, v136, v137
	global_store_dwordx4 v[132:133], v[128:131], off
	s_nop 1
	v_cvt_pk_bf16_f32 v128, v162, v140
	v_cvt_pk_bf16_f32 v129, v141, v142
	v_cvt_pk_bf16_f32 v130, v138, v139
	v_cvt_pk_bf16_f32 v131, v136, v134
